# BRANCH phase rewritten by hand: six chained DMA-staged GEMMs per tile (4x16KiB K=32 stages, 16x16x32 MFMA), register sigmoid/gated accumulate in f32, direct U store
# speedup vs baseline: 1.0522x; 1.0173x over previous
; DI int TID() { int t = (int)__builtin_amdgcn_workitem_id_x(); asm volatile("" : "+v"(t)); return t; }
; DI RowSS rowss_load(const float* ps, int m0) { const int tid = TID(); const float* q = ps + (size_t)(m0 + (tid >> 1)) * 16 + (tid & 1) * 8; RowSS r; r.a = *(const f32x4*)q; r.b = *(const f32x4*)(q + 4); return r; }
; DI void tile_branch(const Params& p, int l, int tile, char* smem) {
;   float* Cs = (float*)smem;
;   const int tid = TID(), lane = tid & 63, w = tid >> 6, wm = w >> 1, wn = w & 1, r32 = lane & 31, hi = lane >> 5;
;   const int mi = tile & (MTN - 1), ni = tile >> MTS; const int m0 = mi * 128, n0 = ni * 128;
;   unsigned upk[2][2][8];
; #pragma unroll
;   for (int a = 0; a < 2; ++a)
; #pragma unroll
;     for (int b = 0; b < 2; ++b)
; #pragma unroll
;       for (int i = 0; i < 8; ++i) upk[a][b][i] = 0u;
;   float* rinv_s = (float*)(smem + SMEM_CS);
;   { const RowSS rss = rowss_load((const float*)(p.ws + OFF_PSIN), m0); rowss_finish(rss, rinv_s); }
; #pragma unroll 1
;   for (int br = 0; br < 3; ++br) {
;     unsigned gpk[2][2][8];
;     {
;       f32x16 accg[2][2]; zero_acc(accg);
;       gemm_main_bf<false, 16>((const u16*)(p.ws + OFF_XB) + (size_t)m0 * 1024, 1024,
;                               (const u16*)(p.ws + OFF_WIN + l * SZ_WIN) + (size_t)(5760 + br * 1024 + n0) * 1024, accg, smem, nullptr);
.LBB1_264:
	s_or_b64 exec, exec, s[26:27]
	v_and_b32_e32 v246, 63, v172
	v_lshrrev_b32_e32 v247, 6, v172
	v_bfe_u32 v166, v246, 4, 2
	v_lshrrev_b32_e32 v167, 1, v166
	v_xor_b32_e32 v166, v166, v167
	v_and_b32_e32 v166, 1, v166
	v_lshl_or_b32 v166, v166, 1, v167
	v_xor_b32_e32 v166, v166, v246
	v_and_b32_e32 v166, 3, v166
	v_lshlrev_b32_e32 v166, 4, v166
	v_lshrrev_b32_e32 v167, 2, v246
	v_lshl_add_u32 v168, v247, 5, v167
	v_lshl_add_u32 v242, v168, 11, v166
	v_add_u32_e32 v243, 0x7c00, v242
	v_lshl_add_u32 v244, v168, 10, v166
	v_add_u32_e32 v245, 0x3c00, v244
	v_readfirstlane_b32 s52, v247
	s_lshl_b32 s52, s52, 11
	s_add_u32 s53, s52, 0x2000
	v_bfe_u32 v166, v246, 2, 2
	v_lshrrev_b32_e32 v167, 1, v166
	v_xor_b32_e32 v166, v166, v167
	v_and_b32_e32 v166, 1, v166
	v_lshl_or_b32 v166, v166, 1, v167
	v_lshrrev_b32_e32 v171, 4, v246
	v_xor_b32_e32 v166, v166, v171
	v_lshlrev_b32_e32 v166, 4, v166
	v_and_b32_e32 v169, 15, v246
	v_lshl_add_u32 v170, v169, 6, v166
	v_lshrrev_b32_e32 v166, 1, v247
	v_and_b32_e32 v167, 1, v247
	v_lshl_add_u32 v240, v166, 12, v170
	v_lshl_add_u32 v241, v167, 12, v170
	v_add_u32_e32 v241, 0x2000, v241
	v_lshl_add_u32 v248, v166, 6, v169
	v_lshlrev_b32_e32 v250, 2, v248
	v_add_u32_e32 v250, 0x12000, v250
	v_lshlrev_b32_e32 v167, 6, v167
	v_lshl_add_u32 v167, v171, 2, v167
	s_and_b32 s12, s17, 0xffffff80
	v_add_u32_e32 v167, s12, v167
	v_add_u32_e32 v168, s16, v248
	v_lshlrev_b32_e32 v249, 11, v168
	v_lshl_add_u32 v249, v167, 1, v249
	s_lshl_b32 s0, s16, 11
	s_add_u32 s44, s34, s0
	s_addc_u32 s45, s35, 0
	s_add_i32 s0, s12, 0x1680
	s_lshl_b32 s0, s0, 11
	s_add_u32 s46, s93, s0
	s_addc_u32 s47, s42, 0
	s_lshl_b32 s0, s16, 10
	s_add_u32 s48, s18, s96
	s_addc_u32 s49, s19, 0
	s_add_u32 s48, s48, s0
	s_addc_u32 s49, s49, 0
	s_add_u32 s50, s18, s97
	s_addc_u32 s51, s19, 0
	s_add_u32 s50, s50, s24
	s_addc_u32 s51, s51, s25
	s_lshl_b32 s0, s12, 10
	s_add_u32 s50, s50, s0
	s_addc_u32 s51, s51, 0
	s_mov_b64 s[28:29], s[44:45]
	s_mov_b64 s[30:31], s[46:47]
	s_add_u32 m0, s52, 0x0
	s_nop 0
	global_load_lds_dwordx4 v242, s[28:29]
	global_load_lds_dwordx4 v243, s[28:29] offset:1024
	s_add_u32 m0, s53, 0x0
	s_nop 0
	global_load_lds_dwordx4 v242, s[30:31]
	global_load_lds_dwordx4 v243, s[30:31] offset:1024
	s_add_u32 m0, s52, 0x4000
	s_add_u32 s28, s28, 0x40
	s_addc_u32 s29, s29, 0
	global_load_lds_dwordx4 v242, s[28:29]
	global_load_lds_dwordx4 v243, s[28:29] offset:1024
	s_add_u32 m0, s53, 0x4000
	s_add_u32 s30, s30, 0x40
	s_addc_u32 s31, s31, 0
	global_load_lds_dwordx4 v242, s[30:31]
	global_load_lds_dwordx4 v243, s[30:31] offset:1024
	s_add_u32 m0, s52, 0x8000
	s_add_u32 s28, s28, 0x40
	s_addc_u32 s29, s29, 0
	global_load_lds_dwordx4 v242, s[28:29]
	global_load_lds_dwordx4 v243, s[28:29] offset:1024
	s_add_u32 m0, s53, 0x8000
	s_add_u32 s30, s30, 0x40
	s_addc_u32 s31, s31, 0
	global_load_lds_dwordx4 v242, s[30:31]
	global_load_lds_dwordx4 v243, s[30:31] offset:1024
	v_mov_b32_e32 v66, 0
	v_mov_b32_e32 v67, 0
	v_mov_b32_e32 v68, 0
	v_mov_b32_e32 v69, 0
	v_mov_b32_e32 v70, 0
	v_mov_b32_e32 v71, 0
	v_mov_b32_e32 v72, 0
	v_mov_b32_e32 v73, 0
	v_mov_b32_e32 v74, 0
	v_mov_b32_e32 v75, 0
	v_mov_b32_e32 v76, 0
	v_mov_b32_e32 v77, 0
	v_mov_b32_e32 v78, 0
	v_mov_b32_e32 v79, 0
	v_mov_b32_e32 v80, 0
	v_mov_b32_e32 v81, 0
	v_mov_b32_e32 v82, 0
	v_mov_b32_e32 v83, 0
	v_mov_b32_e32 v84, 0
	v_mov_b32_e32 v85, 0
	v_mov_b32_e32 v86, 0
	v_mov_b32_e32 v87, 0
	v_mov_b32_e32 v88, 0
	v_mov_b32_e32 v89, 0
	v_mov_b32_e32 v90, 0
	v_mov_b32_e32 v91, 0
	v_mov_b32_e32 v92, 0
	v_mov_b32_e32 v93, 0
	v_mov_b32_e32 v94, 0
	v_mov_b32_e32 v95, 0
	v_mov_b32_e32 v96, 0
	v_mov_b32_e32 v97, 0
	v_mov_b32_e32 v98, 0
	v_mov_b32_e32 v99, 0
	v_mov_b32_e32 v100, 0
	v_mov_b32_e32 v101, 0
	v_mov_b32_e32 v102, 0
	v_mov_b32_e32 v103, 0
	v_mov_b32_e32 v104, 0
	v_mov_b32_e32 v105, 0
	v_mov_b32_e32 v106, 0
	v_mov_b32_e32 v107, 0
	v_mov_b32_e32 v108, 0
	v_mov_b32_e32 v109, 0
	v_mov_b32_e32 v110, 0
	v_mov_b32_e32 v111, 0
	v_mov_b32_e32 v112, 0
	v_mov_b32_e32 v113, 0
	v_mov_b32_e32 v114, 0
	v_mov_b32_e32 v115, 0
	v_mov_b32_e32 v116, 0
	v_mov_b32_e32 v117, 0
	v_mov_b32_e32 v118, 0
	v_mov_b32_e32 v119, 0
	v_mov_b32_e32 v120, 0
	v_mov_b32_e32 v121, 0
	v_mov_b32_e32 v122, 0
	v_mov_b32_e32 v123, 0
	v_mov_b32_e32 v124, 0
	v_mov_b32_e32 v125, 0
	v_mov_b32_e32 v126, 0
	v_mov_b32_e32 v127, 0
	v_mov_b32_e32 v128, 0
	v_mov_b32_e32 v129, 0
	s_mov_b32 s75, 0
.Lbr_loop:
	v_mov_b32_e32 v2, 0
	v_mov_b32_e32 v3, 0
	v_mov_b32_e32 v4, 0
	v_mov_b32_e32 v5, 0
	v_mov_b32_e32 v6, 0
	v_mov_b32_e32 v7, 0
	v_mov_b32_e32 v8, 0
	v_mov_b32_e32 v9, 0
	v_mov_b32_e32 v10, 0
	v_mov_b32_e32 v11, 0
	v_mov_b32_e32 v12, 0
	v_mov_b32_e32 v13, 0
	v_mov_b32_e32 v14, 0
	v_mov_b32_e32 v15, 0
	v_mov_b32_e32 v16, 0
	v_mov_b32_e32 v17, 0
	v_mov_b32_e32 v18, 0
	v_mov_b32_e32 v19, 0
	v_mov_b32_e32 v20, 0
	v_mov_b32_e32 v21, 0
	v_mov_b32_e32 v22, 0
	v_mov_b32_e32 v23, 0
	v_mov_b32_e32 v24, 0
	v_mov_b32_e32 v25, 0
	v_mov_b32_e32 v26, 0
	v_mov_b32_e32 v27, 0
	v_mov_b32_e32 v28, 0
	v_mov_b32_e32 v29, 0
	v_mov_b32_e32 v30, 0
	v_mov_b32_e32 v31, 0
	v_mov_b32_e32 v32, 0
	v_mov_b32_e32 v33, 0
	v_mov_b32_e32 v34, 0
	v_mov_b32_e32 v35, 0
	v_mov_b32_e32 v36, 0
	v_mov_b32_e32 v37, 0
	v_mov_b32_e32 v38, 0
	v_mov_b32_e32 v39, 0
	v_mov_b32_e32 v40, 0
	v_mov_b32_e32 v41, 0
	v_mov_b32_e32 v42, 0
	v_mov_b32_e32 v43, 0
	v_mov_b32_e32 v44, 0
	v_mov_b32_e32 v45, 0
	v_mov_b32_e32 v46, 0
	v_mov_b32_e32 v47, 0
	v_mov_b32_e32 v48, 0
	v_mov_b32_e32 v49, 0
	v_mov_b32_e32 v50, 0
	v_mov_b32_e32 v51, 0
	v_mov_b32_e32 v52, 0
	v_mov_b32_e32 v53, 0
	v_mov_b32_e32 v54, 0
	v_mov_b32_e32 v55, 0
	v_mov_b32_e32 v56, 0
	v_mov_b32_e32 v57, 0
	v_mov_b32_e32 v58, 0
	v_mov_b32_e32 v59, 0
	v_mov_b32_e32 v60, 0
	v_mov_b32_e32 v61, 0
	v_mov_b32_e32 v62, 0
	v_mov_b32_e32 v63, 0
	v_mov_b32_e32 v64, 0
	v_mov_b32_e32 v65, 0
	s_mov_b32 s74, 7
; #define BLOAD(A_, B_, kt) do { _Pragma("unroll") for (int i = 0; i < 4; ++i) { \
;     A_[i] = *(const u32x4*)((const char*)Ap + (aoff + (unsigned)(32 * i * lda + (kt) * 64) * 2u)); B_[i] = *(const u32x4*)((const char*)Wt + (woff + (unsigned)(32 * i * K + (kt) * 64) * 2u)); } } while (0)
; #define BLOAD(A_, B_, kt) do { _Pragma("unroll") for (int i = 0; i < 4; ++i) { \
;     A_[i] = *(const u32x4*)((const char*)Ap + (aoff + (unsigned)(32 * i * lda + (kt) * 64) * 2u)); B_[i] = *(const u32x4*)((const char*)Wt + (woff + (unsigned)(32 * i * K + (kt) * 64) * 2u)); } } while (0)
; #define BSTORE(A_, B_, buf) do { _Pragma("unroll") for (int i = 0; i < 4; ++i) { \
;     *(u32x4*)&As[(buf) * GBUF + (srow + 32 * i) * LDT + sc8] = A_[i]; \
;     *(u32x4*)&Bs[(buf) * GBUF + (srow + 32 * i) * LDT + sc8] = B_[i]; } } while (0)
; template <bool ROWNORM, int NK>
; DI void gemm_main_bf(const u16* __restrict__ Ap, int lda, const u16* __restrict__ Wt, f32x16 (&acc)[2][2], char* smem, float* rinv_s) {
;     ...
;   __builtin_amdgcn_s_setprio(0);
;   BLOAD(a0, b0, 0); BLOAD(a1, b1, 1);
;   __syncthreads();
;   BSTORE(a0, b0, 0);
;   BLOAD(a0, b0, 2);
;   __syncthreads();
; #pragma unroll
;   for (int kt = 0; kt < nk; kt += 2) {
;     BCOMP(0);
;     BSTORE(a1, b1, 1);
;     if (kt + 3 < nk) BLOAD(a1, b1, kt + 3);
;     __syncthreads();
;     BCOMP(1);
;     if (kt + 2 < nk) { BSTORE(a0, b0, 0); if (kt + 4 < nk) BLOAD(a0, b0, kt + 4); }
;     __syncthreads();
;   }
.Lbr_gate_k:
	s_waitcnt vmcnt(8)
	s_barrier
	ds_read_b128 v[208:211], v240 offset:0
	ds_read_b128 v[224:227], v241 offset:0
	ds_read_b128 v[228:231], v241 offset:1024
	ds_read_b128 v[232:235], v241 offset:2048
	ds_read_b128 v[236:239], v241 offset:3072
	s_add_u32 m0, s52, 0xc000
	s_add_u32 s28, s28, 0x40
	s_addc_u32 s29, s29, 0
	global_load_lds_dwordx4 v242, s[28:29]
	global_load_lds_dwordx4 v243, s[28:29] offset:1024
	s_add_u32 m0, s53, 0xc000
	s_add_u32 s30, s30, 0x40
	s_addc_u32 s31, s31, 0
	global_load_lds_dwordx4 v242, s[30:31]
	global_load_lds_dwordx4 v243, s[30:31] offset:1024
	ds_read_b128 v[212:215], v240 offset:1024
	ds_read_b128 v[216:219], v240 offset:2048
	ds_read_b128 v[220:223], v240 offset:3072
	s_waitcnt lgkmcnt(6)
	v_mfma_f32_16x16x32_bf16 v[2:5], v[224:227], v[208:211], v[2:5]
	s_waitcnt lgkmcnt(5)
	v_mfma_f32_16x16x32_bf16 v[6:9], v[228:231], v[208:211], v[6:9]
	s_waitcnt lgkmcnt(4)
	v_mfma_f32_16x16x32_bf16 v[10:13], v[232:235], v[208:211], v[10:13]
	s_waitcnt lgkmcnt(3)
	v_mfma_f32_16x16x32_bf16 v[14:17], v[236:239], v[208:211], v[14:17]
	s_waitcnt lgkmcnt(2)
	v_mfma_f32_16x16x32_bf16 v[18:21], v[224:227], v[212:215], v[18:21]
	v_mfma_f32_16x16x32_bf16 v[22:25], v[228:231], v[212:215], v[22:25]
	v_mfma_f32_16x16x32_bf16 v[26:29], v[232:235], v[212:215], v[26:29]
	v_mfma_f32_16x16x32_bf16 v[30:33], v[236:239], v[212:215], v[30:33]
	s_waitcnt lgkmcnt(1)
	v_mfma_f32_16x16x32_bf16 v[34:37], v[224:227], v[216:219], v[34:37]
	v_mfma_f32_16x16x32_bf16 v[38:41], v[228:231], v[216:219], v[38:41]
	v_mfma_f32_16x16x32_bf16 v[42:45], v[232:235], v[216:219], v[42:45]
	v_mfma_f32_16x16x32_bf16 v[46:49], v[236:239], v[216:219], v[46:49]
	s_waitcnt lgkmcnt(0)
	v_mfma_f32_16x16x32_bf16 v[50:53], v[224:227], v[220:223], v[50:53]
	v_mfma_f32_16x16x32_bf16 v[54:57], v[228:231], v[220:223], v[54:57]
	v_mfma_f32_16x16x32_bf16 v[58:61], v[232:235], v[220:223], v[58:61]
	v_mfma_f32_16x16x32_bf16 v[62:65], v[236:239], v[220:223], v[62:65]
	s_waitcnt vmcnt(8)
	s_barrier
	ds_read_b128 v[208:211], v240 offset:16384
	ds_read_b128 v[224:227], v241 offset:16384
	ds_read_b128 v[228:231], v241 offset:17408
	ds_read_b128 v[232:235], v241 offset:18432
	ds_read_b128 v[236:239], v241 offset:19456
	s_add_u32 m0, s52, 0x0
	s_add_u32 s28, s28, 0x40
	s_addc_u32 s29, s29, 0
	global_load_lds_dwordx4 v242, s[28:29]
	global_load_lds_dwordx4 v243, s[28:29] offset:1024
	s_add_u32 m0, s53, 0x0
	s_add_u32 s30, s30, 0x40
	s_addc_u32 s31, s31, 0
	global_load_lds_dwordx4 v242, s[30:31]
	global_load_lds_dwordx4 v243, s[30:31] offset:1024
	ds_read_b128 v[212:215], v240 offset:17408
	ds_read_b128 v[216:219], v240 offset:18432
	ds_read_b128 v[220:223], v240 offset:19456
	s_waitcnt lgkmcnt(6)
	v_mfma_f32_16x16x32_bf16 v[2:5], v[224:227], v[208:211], v[2:5]
	s_waitcnt lgkmcnt(5)
	v_mfma_f32_16x16x32_bf16 v[6:9], v[228:231], v[208:211], v[6:9]
	s_waitcnt lgkmcnt(4)
	v_mfma_f32_16x16x32_bf16 v[10:13], v[232:235], v[208:211], v[10:13]
	s_waitcnt lgkmcnt(3)
	v_mfma_f32_16x16x32_bf16 v[14:17], v[236:239], v[208:211], v[14:17]
	s_waitcnt lgkmcnt(2)
	v_mfma_f32_16x16x32_bf16 v[18:21], v[224:227], v[212:215], v[18:21]
	v_mfma_f32_16x16x32_bf16 v[22:25], v[228:231], v[212:215], v[22:25]
	v_mfma_f32_16x16x32_bf16 v[26:29], v[232:235], v[212:215], v[26:29]
	v_mfma_f32_16x16x32_bf16 v[30:33], v[236:239], v[212:215], v[30:33]
	s_waitcnt lgkmcnt(1)
	v_mfma_f32_16x16x32_bf16 v[34:37], v[224:227], v[216:219], v[34:37]
	v_mfma_f32_16x16x32_bf16 v[38:41], v[228:231], v[216:219], v[38:41]
	v_mfma_f32_16x16x32_bf16 v[42:45], v[232:235], v[216:219], v[42:45]
	v_mfma_f32_16x16x32_bf16 v[46:49], v[236:239], v[216:219], v[46:49]
	s_waitcnt lgkmcnt(0)
	v_mfma_f32_16x16x32_bf16 v[50:53], v[224:227], v[220:223], v[50:53]
	v_mfma_f32_16x16x32_bf16 v[54:57], v[228:231], v[220:223], v[54:57]
	v_mfma_f32_16x16x32_bf16 v[58:61], v[232:235], v[220:223], v[58:61]
	v_mfma_f32_16x16x32_bf16 v[62:65], v[236:239], v[220:223], v[62:65]
	s_waitcnt vmcnt(8)
	s_barrier
	ds_read_b128 v[208:211], v240 offset:32768
	ds_read_b128 v[224:227], v241 offset:32768
	ds_read_b128 v[228:231], v241 offset:33792
	ds_read_b128 v[232:235], v241 offset:34816
	ds_read_b128 v[236:239], v241 offset:35840
	s_add_u32 m0, s52, 0x4000
	s_add_u32 s28, s28, 0x40
	s_addc_u32 s29, s29, 0
	global_load_lds_dwordx4 v242, s[28:29]
	global_load_lds_dwordx4 v243, s[28:29] offset:1024
	s_add_u32 m0, s53, 0x4000
	s_add_u32 s30, s30, 0x40
	s_addc_u32 s31, s31, 0
	global_load_lds_dwordx4 v242, s[30:31]
	global_load_lds_dwordx4 v243, s[30:31] offset:1024
	ds_read_b128 v[212:215], v240 offset:33792
	ds_read_b128 v[216:219], v240 offset:34816
	ds_read_b128 v[220:223], v240 offset:35840
	s_waitcnt lgkmcnt(6)
	v_mfma_f32_16x16x32_bf16 v[2:5], v[224:227], v[208:211], v[2:5]
	s_waitcnt lgkmcnt(5)
	v_mfma_f32_16x16x32_bf16 v[6:9], v[228:231], v[208:211], v[6:9]
	s_waitcnt lgkmcnt(4)
	v_mfma_f32_16x16x32_bf16 v[10:13], v[232:235], v[208:211], v[10:13]
	s_waitcnt lgkmcnt(3)
	v_mfma_f32_16x16x32_bf16 v[14:17], v[236:239], v[208:211], v[14:17]
	s_waitcnt lgkmcnt(2)
	v_mfma_f32_16x16x32_bf16 v[18:21], v[224:227], v[212:215], v[18:21]
	v_mfma_f32_16x16x32_bf16 v[22:25], v[228:231], v[212:215], v[22:25]
	v_mfma_f32_16x16x32_bf16 v[26:29], v[232:235], v[212:215], v[26:29]
	v_mfma_f32_16x16x32_bf16 v[30:33], v[236:239], v[212:215], v[30:33]
	s_waitcnt lgkmcnt(1)
	v_mfma_f32_16x16x32_bf16 v[34:37], v[224:227], v[216:219], v[34:37]
	v_mfma_f32_16x16x32_bf16 v[38:41], v[228:231], v[216:219], v[38:41]
	v_mfma_f32_16x16x32_bf16 v[42:45], v[232:235], v[216:219], v[42:45]
	v_mfma_f32_16x16x32_bf16 v[46:49], v[236:239], v[216:219], v[46:49]
	s_waitcnt lgkmcnt(0)
	v_mfma_f32_16x16x32_bf16 v[50:53], v[224:227], v[220:223], v[50:53]
	v_mfma_f32_16x16x32_bf16 v[54:57], v[228:231], v[220:223], v[54:57]
	v_mfma_f32_16x16x32_bf16 v[58:61], v[232:235], v[220:223], v[58:61]
	v_mfma_f32_16x16x32_bf16 v[62:65], v[236:239], v[220:223], v[62:65]
	s_waitcnt vmcnt(8)
	s_barrier
; #define BLOAD(A_, B_, kt) do { _Pragma("unroll") for (int i = 0; i < 4; ++i) { \
;     A_[i] = *(const u32x4*)((const char*)Ap + (aoff + (unsigned)(32 * i * lda + (kt) * 64) * 2u)); B_[i] = *(const u32x4*)((const char*)Wt + (woff + (unsigned)(32 * i * K + (kt) * 64) * 2u)); } } while (0)
; #define BLOAD(A_, B_, kt) do { _Pragma("unroll") for (int i = 0; i < 4; ++i) { \
;     A_[i] = *(const u32x4*)((const char*)Ap + (aoff + (unsigned)(32 * i * lda + (kt) * 64) * 2u)); B_[i] = *(const u32x4*)((const char*)Wt + (woff + (unsigned)(32 * i * K + (kt) * 64) * 2u)); } } while (0)
; #define BSTORE(A_, B_, buf) do { _Pragma("unroll") for (int i = 0; i < 4; ++i) { \
;     *(u32x4*)&As[(buf) * GBUF + (srow + 32 * i) * LDT + sc8] = A_[i]; \
;     *(u32x4*)&Bs[(buf) * GBUF + (srow + 32 * i) * LDT + sc8] = B_[i]; } } while (0)
; template <bool ROWNORM, int NK>
; DI void gemm_main_bf(const u16* __restrict__ Ap, int lda, const u16* __restrict__ Wt, f32x16 (&acc)[2][2], char* smem, float* rinv_s) {
;     ...
;   __builtin_amdgcn_s_setprio(0);
;   BLOAD(a0, b0, 0); BLOAD(a1, b1, 1);
;   __syncthreads();
;   BSTORE(a0, b0, 0);
;   BLOAD(a0, b0, 2);
;   __syncthreads();
; #pragma unroll
;   for (int kt = 0; kt < nk; kt += 2) {
;     BCOMP(0);
;     BSTORE(a1, b1, 1);
;     if (kt + 3 < nk) BLOAD(a1, b1, kt + 3);
;     __syncthreads();
;     BCOMP(1);
;     if (kt + 2 < nk) { BSTORE(a0, b0, 0); if (kt + 4 < nk) BLOAD(a0, b0, kt + 4); }
;     __syncthreads();
;   }
	ds_read_b128 v[208:211], v240 offset:49152
	ds_read_b128 v[224:227], v241 offset:49152
	ds_read_b128 v[228:231], v241 offset:50176
	ds_read_b128 v[232:235], v241 offset:51200
	ds_read_b128 v[236:239], v241 offset:52224
	s_add_u32 m0, s52, 0x8000
	s_add_u32 s28, s28, 0x40
	s_addc_u32 s29, s29, 0
	global_load_lds_dwordx4 v242, s[28:29]
	global_load_lds_dwordx4 v243, s[28:29] offset:1024
	s_add_u32 m0, s53, 0x8000
	s_add_u32 s30, s30, 0x40
	s_addc_u32 s31, s31, 0
	global_load_lds_dwordx4 v242, s[30:31]
	global_load_lds_dwordx4 v243, s[30:31] offset:1024
	ds_read_b128 v[212:215], v240 offset:50176
	ds_read_b128 v[216:219], v240 offset:51200
	ds_read_b128 v[220:223], v240 offset:52224
	s_waitcnt lgkmcnt(6)
	v_mfma_f32_16x16x32_bf16 v[2:5], v[224:227], v[208:211], v[2:5]
	s_waitcnt lgkmcnt(5)
	v_mfma_f32_16x16x32_bf16 v[6:9], v[228:231], v[208:211], v[6:9]
	s_waitcnt lgkmcnt(4)
	v_mfma_f32_16x16x32_bf16 v[10:13], v[232:235], v[208:211], v[10:13]
	s_waitcnt lgkmcnt(3)
	v_mfma_f32_16x16x32_bf16 v[14:17], v[236:239], v[208:211], v[14:17]
	s_waitcnt lgkmcnt(2)
	v_mfma_f32_16x16x32_bf16 v[18:21], v[224:227], v[212:215], v[18:21]
	v_mfma_f32_16x16x32_bf16 v[22:25], v[228:231], v[212:215], v[22:25]
	v_mfma_f32_16x16x32_bf16 v[26:29], v[232:235], v[212:215], v[26:29]
	v_mfma_f32_16x16x32_bf16 v[30:33], v[236:239], v[212:215], v[30:33]
	s_waitcnt lgkmcnt(1)
	v_mfma_f32_16x16x32_bf16 v[34:37], v[224:227], v[216:219], v[34:37]
	v_mfma_f32_16x16x32_bf16 v[38:41], v[228:231], v[216:219], v[38:41]
	v_mfma_f32_16x16x32_bf16 v[42:45], v[232:235], v[216:219], v[42:45]
	v_mfma_f32_16x16x32_bf16 v[46:49], v[236:239], v[216:219], v[46:49]
	s_waitcnt lgkmcnt(0)
	v_mfma_f32_16x16x32_bf16 v[50:53], v[224:227], v[220:223], v[50:53]
	v_mfma_f32_16x16x32_bf16 v[54:57], v[228:231], v[220:223], v[54:57]
	v_mfma_f32_16x16x32_bf16 v[58:61], v[232:235], v[220:223], v[58:61]
	v_mfma_f32_16x16x32_bf16 v[62:65], v[236:239], v[220:223], v[62:65]
	s_sub_u32 s74, s74, 1
	s_cmp_lg_u32 s74, 0
	s_cbranch_scc1 .Lbr_gate_k
	s_waitcnt vmcnt(8)
	s_barrier
	ds_read_b128 v[208:211], v240 offset:0
	ds_read_b128 v[224:227], v241 offset:0
	ds_read_b128 v[228:231], v241 offset:1024
	ds_read_b128 v[232:235], v241 offset:2048
	ds_read_b128 v[236:239], v241 offset:3072
	s_add_u32 m0, s52, 0xc000
	s_add_u32 s28, s28, 0x40
	s_addc_u32 s29, s29, 0
	global_load_lds_dwordx4 v242, s[28:29]
	global_load_lds_dwordx4 v243, s[28:29] offset:1024
	s_add_u32 m0, s53, 0xc000
	s_add_u32 s30, s30, 0x40
	s_addc_u32 s31, s31, 0
	global_load_lds_dwordx4 v242, s[30:31]
	global_load_lds_dwordx4 v243, s[30:31] offset:1024
	ds_read_b128 v[212:215], v240 offset:1024
	ds_read_b128 v[216:219], v240 offset:2048
	ds_read_b128 v[220:223], v240 offset:3072
	s_waitcnt lgkmcnt(6)
	v_mfma_f32_16x16x32_bf16 v[2:5], v[224:227], v[208:211], v[2:5]
	s_waitcnt lgkmcnt(5)
	v_mfma_f32_16x16x32_bf16 v[6:9], v[228:231], v[208:211], v[6:9]
	s_waitcnt lgkmcnt(4)
	v_mfma_f32_16x16x32_bf16 v[10:13], v[232:235], v[208:211], v[10:13]
	s_waitcnt lgkmcnt(3)
	v_mfma_f32_16x16x32_bf16 v[14:17], v[236:239], v[208:211], v[14:17]
	s_waitcnt lgkmcnt(2)
	v_mfma_f32_16x16x32_bf16 v[18:21], v[224:227], v[212:215], v[18:21]
	v_mfma_f32_16x16x32_bf16 v[22:25], v[228:231], v[212:215], v[22:25]
	v_mfma_f32_16x16x32_bf16 v[26:29], v[232:235], v[212:215], v[26:29]
	v_mfma_f32_16x16x32_bf16 v[30:33], v[236:239], v[212:215], v[30:33]
	s_waitcnt lgkmcnt(1)
	v_mfma_f32_16x16x32_bf16 v[34:37], v[224:227], v[216:219], v[34:37]
	v_mfma_f32_16x16x32_bf16 v[38:41], v[228:231], v[216:219], v[38:41]
	v_mfma_f32_16x16x32_bf16 v[42:45], v[232:235], v[216:219], v[42:45]
	v_mfma_f32_16x16x32_bf16 v[46:49], v[236:239], v[216:219], v[46:49]
	s_waitcnt lgkmcnt(0)
	v_mfma_f32_16x16x32_bf16 v[50:53], v[224:227], v[220:223], v[50:53]
	v_mfma_f32_16x16x32_bf16 v[54:57], v[228:231], v[220:223], v[54:57]
	v_mfma_f32_16x16x32_bf16 v[58:61], v[232:235], v[220:223], v[58:61]
	v_mfma_f32_16x16x32_bf16 v[62:65], v[236:239], v[220:223], v[62:65]
	s_waitcnt vmcnt(8)
	s_barrier
	ds_read_b128 v[208:211], v240 offset:16384
	ds_read_b128 v[224:227], v241 offset:16384
	ds_read_b128 v[228:231], v241 offset:17408
	ds_read_b128 v[232:235], v241 offset:18432
	ds_read_b128 v[236:239], v241 offset:19456
	ds_read_b128 v[212:215], v240 offset:17408
	ds_read_b128 v[216:219], v240 offset:18432
	ds_read_b128 v[220:223], v240 offset:19456
	s_waitcnt lgkmcnt(6)
	v_mfma_f32_16x16x32_bf16 v[2:5], v[224:227], v[208:211], v[2:5]
	s_waitcnt lgkmcnt(5)
	v_mfma_f32_16x16x32_bf16 v[6:9], v[228:231], v[208:211], v[6:9]
	s_waitcnt lgkmcnt(4)
	v_mfma_f32_16x16x32_bf16 v[10:13], v[232:235], v[208:211], v[10:13]
	s_waitcnt lgkmcnt(3)
	v_mfma_f32_16x16x32_bf16 v[14:17], v[236:239], v[208:211], v[14:17]
	s_waitcnt lgkmcnt(2)
	v_mfma_f32_16x16x32_bf16 v[18:21], v[224:227], v[212:215], v[18:21]
	v_mfma_f32_16x16x32_bf16 v[22:25], v[228:231], v[212:215], v[22:25]
	v_mfma_f32_16x16x32_bf16 v[26:29], v[232:235], v[212:215], v[26:29]
	v_mfma_f32_16x16x32_bf16 v[30:33], v[236:239], v[212:215], v[30:33]
	s_waitcnt lgkmcnt(1)
	v_mfma_f32_16x16x32_bf16 v[34:37], v[224:227], v[216:219], v[34:37]
	v_mfma_f32_16x16x32_bf16 v[38:41], v[228:231], v[216:219], v[38:41]
	v_mfma_f32_16x16x32_bf16 v[42:45], v[232:235], v[216:219], v[42:45]
	v_mfma_f32_16x16x32_bf16 v[46:49], v[236:239], v[216:219], v[46:49]
	s_waitcnt lgkmcnt(0)
	v_mfma_f32_16x16x32_bf16 v[50:53], v[224:227], v[220:223], v[50:53]
	v_mfma_f32_16x16x32_bf16 v[54:57], v[228:231], v[220:223], v[54:57]
	v_mfma_f32_16x16x32_bf16 v[58:61], v[232:235], v[220:223], v[58:61]
	v_mfma_f32_16x16x32_bf16 v[62:65], v[236:239], v[220:223], v[62:65]
	s_waitcnt vmcnt(4)
	s_barrier
; #define BLOAD(A_, B_, kt) do { _Pragma("unroll") for (int i = 0; i < 4; ++i) { \
;     A_[i] = *(const u32x4*)((const char*)Ap + (aoff + (unsigned)(32 * i * lda + (kt) * 64) * 2u)); B_[i] = *(const u32x4*)((const char*)Wt + (woff + (unsigned)(32 * i * K + (kt) * 64) * 2u)); } } while (0)
; #define BLOAD(A_, B_, kt) do { _Pragma("unroll") for (int i = 0; i < 4; ++i) { \
;     A_[i] = *(const u32x4*)((const char*)Ap + (aoff + (unsigned)(32 * i * lda + (kt) * 64) * 2u)); B_[i] = *(const u32x4*)((const char*)Wt + (woff + (unsigned)(32 * i * K + (kt) * 64) * 2u)); } } while (0)
; #define BSTORE(A_, B_, buf) do { _Pragma("unroll") for (int i = 0; i < 4; ++i) { \
;     *(u32x4*)&As[(buf) * GBUF + (srow + 32 * i) * LDT + sc8] = A_[i]; \
;     *(u32x4*)&Bs[(buf) * GBUF + (srow + 32 * i) * LDT + sc8] = B_[i]; } } while (0)
; template <bool ROWNORM, int NK>
; DI void gemm_main_bf(const u16* __restrict__ Ap, int lda, const u16* __restrict__ Wt, f32x16 (&acc)[2][2], char* smem, float* rinv_s) {
;     ...
; #pragma unroll
;   for (int kt = 0; kt < nk; kt += 2) {
;     BCOMP(0);
;     BSTORE(a1, b1, 1);
;     if (kt + 3 < nk) BLOAD(a1, b1, kt + 3);
;     __syncthreads();
;     BCOMP(1);
;     if (kt + 2 < nk) { BSTORE(a0, b0, 0); if (kt + 4 < nk) BLOAD(a0, b0, kt + 4); }
;     __syncthreads();
;   }
; DI void tile_branch(const Params& p, int l, int tile, char* smem) {
;     ...
;       __syncthreads();
; #pragma unroll
;       for (int mt = 0; mt < 2; ++mt)
; #pragma unroll
;         for (int g4 = 0; g4 < 4; ++g4) {
;           const f32x4 r4 = *(const f32x4*)&rinv_s[wm * 64 + mt * 32 + 8 * g4 + 4 * hi];
	ds_read_b128 v[208:211], v240 offset:32768
	ds_read_b128 v[224:227], v241 offset:32768
	ds_read_b128 v[228:231], v241 offset:33792
	ds_read_b128 v[232:235], v241 offset:34816
	ds_read_b128 v[236:239], v241 offset:35840
	ds_read_b128 v[212:215], v240 offset:33792
	ds_read_b128 v[216:219], v240 offset:34816
	ds_read_b128 v[220:223], v240 offset:35840
	s_waitcnt lgkmcnt(6)
	v_mfma_f32_16x16x32_bf16 v[2:5], v[224:227], v[208:211], v[2:5]
	s_waitcnt lgkmcnt(5)
	v_mfma_f32_16x16x32_bf16 v[6:9], v[228:231], v[208:211], v[6:9]
	s_waitcnt lgkmcnt(4)
	v_mfma_f32_16x16x32_bf16 v[10:13], v[232:235], v[208:211], v[10:13]
	s_waitcnt lgkmcnt(3)
	v_mfma_f32_16x16x32_bf16 v[14:17], v[236:239], v[208:211], v[14:17]
	s_waitcnt lgkmcnt(2)
	v_mfma_f32_16x16x32_bf16 v[18:21], v[224:227], v[212:215], v[18:21]
	v_mfma_f32_16x16x32_bf16 v[22:25], v[228:231], v[212:215], v[22:25]
	v_mfma_f32_16x16x32_bf16 v[26:29], v[232:235], v[212:215], v[26:29]
	v_mfma_f32_16x16x32_bf16 v[30:33], v[236:239], v[212:215], v[30:33]
	s_waitcnt lgkmcnt(1)
	v_mfma_f32_16x16x32_bf16 v[34:37], v[224:227], v[216:219], v[34:37]
	v_mfma_f32_16x16x32_bf16 v[38:41], v[228:231], v[216:219], v[38:41]
	v_mfma_f32_16x16x32_bf16 v[42:45], v[232:235], v[216:219], v[42:45]
	v_mfma_f32_16x16x32_bf16 v[46:49], v[236:239], v[216:219], v[46:49]
	s_waitcnt lgkmcnt(0)
	v_mfma_f32_16x16x32_bf16 v[50:53], v[224:227], v[220:223], v[50:53]
	v_mfma_f32_16x16x32_bf16 v[54:57], v[228:231], v[220:223], v[54:57]
	v_mfma_f32_16x16x32_bf16 v[58:61], v[232:235], v[220:223], v[58:61]
	v_mfma_f32_16x16x32_bf16 v[62:65], v[236:239], v[220:223], v[62:65]
	s_waitcnt vmcnt(0)
	s_barrier
	ds_read_b128 v[208:211], v240 offset:49152
	ds_read_b128 v[224:227], v241 offset:49152
	ds_read_b128 v[228:231], v241 offset:50176
	ds_read_b128 v[232:235], v241 offset:51200
	ds_read_b128 v[236:239], v241 offset:52224
	ds_read_b128 v[212:215], v240 offset:50176
	ds_read_b128 v[216:219], v240 offset:51200
	ds_read_b128 v[220:223], v240 offset:52224
	s_waitcnt lgkmcnt(6)
	v_mfma_f32_16x16x32_bf16 v[2:5], v[224:227], v[208:211], v[2:5]
	s_waitcnt lgkmcnt(5)
	v_mfma_f32_16x16x32_bf16 v[6:9], v[228:231], v[208:211], v[6:9]
	s_waitcnt lgkmcnt(4)
	v_mfma_f32_16x16x32_bf16 v[10:13], v[232:235], v[208:211], v[10:13]
	s_waitcnt lgkmcnt(3)
	v_mfma_f32_16x16x32_bf16 v[14:17], v[236:239], v[208:211], v[14:17]
	s_waitcnt lgkmcnt(2)
	v_mfma_f32_16x16x32_bf16 v[18:21], v[224:227], v[212:215], v[18:21]
	v_mfma_f32_16x16x32_bf16 v[22:25], v[228:231], v[212:215], v[22:25]
	v_mfma_f32_16x16x32_bf16 v[26:29], v[232:235], v[212:215], v[26:29]
	v_mfma_f32_16x16x32_bf16 v[30:33], v[236:239], v[212:215], v[30:33]
	s_waitcnt lgkmcnt(1)
	v_mfma_f32_16x16x32_bf16 v[34:37], v[224:227], v[216:219], v[34:37]
	v_mfma_f32_16x16x32_bf16 v[38:41], v[228:231], v[216:219], v[38:41]
	v_mfma_f32_16x16x32_bf16 v[42:45], v[232:235], v[216:219], v[42:45]
	v_mfma_f32_16x16x32_bf16 v[46:49], v[236:239], v[216:219], v[46:49]
	s_waitcnt lgkmcnt(0)
	v_mfma_f32_16x16x32_bf16 v[50:53], v[224:227], v[220:223], v[50:53]
	v_mfma_f32_16x16x32_bf16 v[54:57], v[228:231], v[220:223], v[54:57]
	v_mfma_f32_16x16x32_bf16 v[58:61], v[232:235], v[220:223], v[58:61]
	v_mfma_f32_16x16x32_bf16 v[62:65], v[236:239], v[220:223], v[62:65]
	s_mov_b64 s[28:29], s[48:49]
	s_mov_b64 s[30:31], s[50:51]
	s_add_u32 m0, s52, 0x0
	s_nop 0
	global_load_lds_dwordx4 v244, s[28:29]
	global_load_lds_dwordx4 v245, s[28:29] offset:1024
	s_add_u32 m0, s53, 0x0
	s_nop 0
	global_load_lds_dwordx4 v244, s[30:31]
	global_load_lds_dwordx4 v245, s[30:31] offset:1024
	s_add_u32 m0, s52, 0x4000
	s_add_u32 s28, s28, 0x40
	s_addc_u32 s29, s29, 0
	global_load_lds_dwordx4 v244, s[28:29]
	global_load_lds_dwordx4 v245, s[28:29] offset:1024
	s_add_u32 m0, s53, 0x4000
	s_add_u32 s30, s30, 0x40
	s_addc_u32 s31, s31, 0
	global_load_lds_dwordx4 v244, s[30:31]
	global_load_lds_dwordx4 v245, s[30:31] offset:1024
	s_add_u32 m0, s52, 0x8000
	s_add_u32 s28, s28, 0x40
	s_addc_u32 s29, s29, 0
	global_load_lds_dwordx4 v244, s[28:29]
	global_load_lds_dwordx4 v245, s[28:29] offset:1024
	s_add_u32 m0, s53, 0x8000
	s_add_u32 s30, s30, 0x40
	s_addc_u32 s31, s31, 0
	global_load_lds_dwordx4 v244, s[30:31]
	global_load_lds_dwordx4 v245, s[30:31] offset:1024
	ds_read_b32 v162, v250 offset:0
	ds_read_b32 v163, v250 offset:64
	ds_read_b32 v164, v250 offset:128
	ds_read_b32 v165, v250 offset:192
	s_waitcnt lgkmcnt(0)
; DI unsigned pk2(float a, float b) { f2_t v = {a, b}; bf2_t r = __builtin_convertvector(v, bf2_t); return __builtin_bit_cast(unsigned, r); }
; DI void tile_branch(const Params& p, int l, int tile, char* smem) {
;     ...
; #pragma unroll
;       for (int mt = 0; mt < 2; ++mt)
; #pragma unroll
;         for (int g4 = 0; g4 < 4; ++g4) {
;           const f32x4 r4 = *(const f32x4*)&rinv_s[wm * 64 + mt * 32 + 8 * g4 + 4 * hi];
; #pragma unroll
;           for (int nt = 0; nt < 2; ++nt) {
;             const float s0 = 1.f / (1.f + __expf(-accg[mt][nt][4 * g4 + 0] * r4[0])), s1 = 1.f / (1.f + __expf(-accg[mt][nt][4 * g4 + 1] * r4[1]));
;             const float s2 = 1.f / (1.f + __expf(-accg[mt][nt][4 * g4 + 2] * r4[2])), s3 = 1.f / (1.f + __expf(-accg[mt][nt][4 * g4 + 3] * r4[3]));
;             gpk[mt][nt][2 * g4] = pk2(s0, s1); gpk[mt][nt][2 * g4 + 1] = pk2(s2, s3);
;           }
;         }
	v_mul_f32_e32 v162, 0xbfb8aa3b, v162
	v_mul_f32_e32 v163, 0xbfb8aa3b, v163
	v_mul_f32_e32 v164, 0xbfb8aa3b, v164
	v_mul_f32_e32 v165, 0xbfb8aa3b, v165
	v_mul_f32_e32 v166, v162, v2
	v_mul_f32_e32 v167, v162, v3
	v_mul_f32_e32 v168, v162, v4
	v_mul_f32_e32 v169, v162, v5
	v_exp_f32_e32 v166, v166
	v_exp_f32_e32 v167, v167
	v_exp_f32_e32 v168, v168
	v_exp_f32_e32 v169, v169
	v_add_f32_e32 v166, 1.0, v166
	v_add_f32_e32 v167, 1.0, v167
	v_add_f32_e32 v168, 1.0, v168
	v_add_f32_e32 v169, 1.0, v169
	v_rcp_f32_e32 v166, v166
	v_rcp_f32_e32 v167, v167
	v_rcp_f32_e32 v168, v168
	v_rcp_f32_e32 v169, v169
	v_cvt_pk_bf16_f32 v130, v166, v167
	v_cvt_pk_bf16_f32 v131, v168, v169
	v_mul_f32_e32 v166, v162, v6
	v_mul_f32_e32 v167, v162, v7
	v_mul_f32_e32 v168, v162, v8
	v_mul_f32_e32 v169, v162, v9
	v_exp_f32_e32 v166, v166
	v_exp_f32_e32 v167, v167
	v_exp_f32_e32 v168, v168
	v_exp_f32_e32 v169, v169
	v_add_f32_e32 v166, 1.0, v166
	v_add_f32_e32 v167, 1.0, v167
	v_add_f32_e32 v168, 1.0, v168
	v_add_f32_e32 v169, 1.0, v169
	v_rcp_f32_e32 v166, v166
	v_rcp_f32_e32 v167, v167
	v_rcp_f32_e32 v168, v168
	v_rcp_f32_e32 v169, v169
	v_cvt_pk_bf16_f32 v132, v166, v167
	v_cvt_pk_bf16_f32 v133, v168, v169
	v_mul_f32_e32 v166, v162, v10
	v_mul_f32_e32 v167, v162, v11
	v_mul_f32_e32 v168, v162, v12
	v_mul_f32_e32 v169, v162, v13
	v_exp_f32_e32 v166, v166
	v_exp_f32_e32 v167, v167
	v_exp_f32_e32 v168, v168
	v_exp_f32_e32 v169, v169
	v_add_f32_e32 v166, 1.0, v166
	v_add_f32_e32 v167, 1.0, v167
	v_add_f32_e32 v168, 1.0, v168
	v_add_f32_e32 v169, 1.0, v169
	v_rcp_f32_e32 v166, v166
	v_rcp_f32_e32 v167, v167
	v_rcp_f32_e32 v168, v168
	v_rcp_f32_e32 v169, v169
	v_cvt_pk_bf16_f32 v134, v166, v167
	v_cvt_pk_bf16_f32 v135, v168, v169
	v_mul_f32_e32 v166, v162, v14
	v_mul_f32_e32 v167, v162, v15
	v_mul_f32_e32 v168, v162, v16
	v_mul_f32_e32 v169, v162, v17
	v_exp_f32_e32 v166, v166
	v_exp_f32_e32 v167, v167
	v_exp_f32_e32 v168, v168
	v_exp_f32_e32 v169, v169
	v_add_f32_e32 v166, 1.0, v166
	v_add_f32_e32 v167, 1.0, v167
	v_add_f32_e32 v168, 1.0, v168
	v_add_f32_e32 v169, 1.0, v169
	v_rcp_f32_e32 v166, v166
	v_rcp_f32_e32 v167, v167
	v_rcp_f32_e32 v168, v168
	v_rcp_f32_e32 v169, v169
	v_cvt_pk_bf16_f32 v136, v166, v167
	v_cvt_pk_bf16_f32 v137, v168, v169
	v_mul_f32_e32 v166, v163, v18
	v_mul_f32_e32 v167, v163, v19
	v_mul_f32_e32 v168, v163, v20
	v_mul_f32_e32 v169, v163, v21
	v_exp_f32_e32 v166, v166
	v_exp_f32_e32 v167, v167
	v_exp_f32_e32 v168, v168
	v_exp_f32_e32 v169, v169
	v_add_f32_e32 v166, 1.0, v166
	v_add_f32_e32 v167, 1.0, v167
	v_add_f32_e32 v168, 1.0, v168
	v_add_f32_e32 v169, 1.0, v169
	v_rcp_f32_e32 v166, v166
	v_rcp_f32_e32 v167, v167
	v_rcp_f32_e32 v168, v168
	v_rcp_f32_e32 v169, v169
	v_cvt_pk_bf16_f32 v138, v166, v167
	v_cvt_pk_bf16_f32 v139, v168, v169
	v_mul_f32_e32 v166, v163, v22
	v_mul_f32_e32 v167, v163, v23
	v_mul_f32_e32 v168, v163, v24
	v_mul_f32_e32 v169, v163, v25
	v_exp_f32_e32 v166, v166
	v_exp_f32_e32 v167, v167
	v_exp_f32_e32 v168, v168
	v_exp_f32_e32 v169, v169
	v_add_f32_e32 v166, 1.0, v166
	v_add_f32_e32 v167, 1.0, v167
	v_add_f32_e32 v168, 1.0, v168
	v_add_f32_e32 v169, 1.0, v169
	v_rcp_f32_e32 v166, v166
	v_rcp_f32_e32 v167, v167
	v_rcp_f32_e32 v168, v168
	v_rcp_f32_e32 v169, v169
	v_cvt_pk_bf16_f32 v140, v166, v167
	v_cvt_pk_bf16_f32 v141, v168, v169
	v_mul_f32_e32 v166, v163, v26
	v_mul_f32_e32 v167, v163, v27
	v_mul_f32_e32 v168, v163, v28
	v_mul_f32_e32 v169, v163, v29
	v_exp_f32_e32 v166, v166
	v_exp_f32_e32 v167, v167
	v_exp_f32_e32 v168, v168
	v_exp_f32_e32 v169, v169
	v_add_f32_e32 v166, 1.0, v166
	v_add_f32_e32 v167, 1.0, v167
	v_add_f32_e32 v168, 1.0, v168
	v_add_f32_e32 v169, 1.0, v169
	v_rcp_f32_e32 v166, v166
	v_rcp_f32_e32 v167, v167
	v_rcp_f32_e32 v168, v168
	v_rcp_f32_e32 v169, v169
	v_cvt_pk_bf16_f32 v142, v166, v167
	v_cvt_pk_bf16_f32 v143, v168, v169
	v_mul_f32_e32 v166, v163, v30
	v_mul_f32_e32 v167, v163, v31
	v_mul_f32_e32 v168, v163, v32
	v_mul_f32_e32 v169, v163, v33
	v_exp_f32_e32 v166, v166
	v_exp_f32_e32 v167, v167
	v_exp_f32_e32 v168, v168
	v_exp_f32_e32 v169, v169
	v_add_f32_e32 v166, 1.0, v166
	v_add_f32_e32 v167, 1.0, v167
	v_add_f32_e32 v168, 1.0, v168
	v_add_f32_e32 v169, 1.0, v169
	v_rcp_f32_e32 v166, v166
	v_rcp_f32_e32 v167, v167
	v_rcp_f32_e32 v168, v168
	v_rcp_f32_e32 v169, v169
	v_cvt_pk_bf16_f32 v144, v166, v167
	v_cvt_pk_bf16_f32 v145, v168, v169
	v_mul_f32_e32 v166, v164, v34
	v_mul_f32_e32 v167, v164, v35
	v_mul_f32_e32 v168, v164, v36
	v_mul_f32_e32 v169, v164, v37
	v_exp_f32_e32 v166, v166
	v_exp_f32_e32 v167, v167
	v_exp_f32_e32 v168, v168
	v_exp_f32_e32 v169, v169
	v_add_f32_e32 v166, 1.0, v166
	v_add_f32_e32 v167, 1.0, v167
	v_add_f32_e32 v168, 1.0, v168
	v_add_f32_e32 v169, 1.0, v169
	v_rcp_f32_e32 v166, v166
	v_rcp_f32_e32 v167, v167
	v_rcp_f32_e32 v168, v168
	v_rcp_f32_e32 v169, v169
	v_cvt_pk_bf16_f32 v146, v166, v167
	v_cvt_pk_bf16_f32 v147, v168, v169
	v_mul_f32_e32 v166, v164, v38
	v_mul_f32_e32 v167, v164, v39
	v_mul_f32_e32 v168, v164, v40
	v_mul_f32_e32 v169, v164, v41
	v_exp_f32_e32 v166, v166
	v_exp_f32_e32 v167, v167
	v_exp_f32_e32 v168, v168
	v_exp_f32_e32 v169, v169
	v_add_f32_e32 v166, 1.0, v166
	v_add_f32_e32 v167, 1.0, v167
	v_add_f32_e32 v168, 1.0, v168
	v_add_f32_e32 v169, 1.0, v169
	v_rcp_f32_e32 v166, v166
	v_rcp_f32_e32 v167, v167
	v_rcp_f32_e32 v168, v168
	v_rcp_f32_e32 v169, v169
	v_cvt_pk_bf16_f32 v148, v166, v167
	v_cvt_pk_bf16_f32 v149, v168, v169
	v_mul_f32_e32 v166, v164, v42
	v_mul_f32_e32 v167, v164, v43
	v_mul_f32_e32 v168, v164, v44
	v_mul_f32_e32 v169, v164, v45
	v_exp_f32_e32 v166, v166
	v_exp_f32_e32 v167, v167
	v_exp_f32_e32 v168, v168
	v_exp_f32_e32 v169, v169
; DI unsigned pk2(float a, float b) { f2_t v = {a, b}; bf2_t r = __builtin_convertvector(v, bf2_t); return __builtin_bit_cast(unsigned, r); }
; DI void tile_branch(const Params& p, int l, int tile, char* smem) {
;     ...
; #pragma unroll
;       for (int mt = 0; mt < 2; ++mt)
; #pragma unroll
;         for (int g4 = 0; g4 < 4; ++g4) {
;           const f32x4 r4 = *(const f32x4*)&rinv_s[wm * 64 + mt * 32 + 8 * g4 + 4 * hi];
; #pragma unroll
;           for (int nt = 0; nt < 2; ++nt) {
;             const float s0 = 1.f / (1.f + __expf(-accg[mt][nt][4 * g4 + 0] * r4[0])), s1 = 1.f / (1.f + __expf(-accg[mt][nt][4 * g4 + 1] * r4[1]));
;             const float s2 = 1.f / (1.f + __expf(-accg[mt][nt][4 * g4 + 2] * r4[2])), s3 = 1.f / (1.f + __expf(-accg[mt][nt][4 * g4 + 3] * r4[3]));
;             gpk[mt][nt][2 * g4] = pk2(s0, s1); gpk[mt][nt][2 * g4 + 1] = pk2(s2, s3);
;           }
;         }
;     }
;     f32x16 acc[2][2]; zero_acc(acc);
;     gemm_main_bf<false, 8>((const u16*)(p.ws + OFF_BR) + (size_t)(br * CT + m0) * 512, 512,
	v_add_f32_e32 v166, 1.0, v166
	v_add_f32_e32 v167, 1.0, v167
	v_add_f32_e32 v168, 1.0, v168
	v_add_f32_e32 v169, 1.0, v169
	v_rcp_f32_e32 v166, v166
	v_rcp_f32_e32 v167, v167
	v_rcp_f32_e32 v168, v168
	v_rcp_f32_e32 v169, v169
	v_cvt_pk_bf16_f32 v150, v166, v167
	v_cvt_pk_bf16_f32 v151, v168, v169
	v_mul_f32_e32 v166, v164, v46
	v_mul_f32_e32 v167, v164, v47
	v_mul_f32_e32 v168, v164, v48
	v_mul_f32_e32 v169, v164, v49
	v_exp_f32_e32 v166, v166
	v_exp_f32_e32 v167, v167
	v_exp_f32_e32 v168, v168
	v_exp_f32_e32 v169, v169
	v_add_f32_e32 v166, 1.0, v166
	v_add_f32_e32 v167, 1.0, v167
	v_add_f32_e32 v168, 1.0, v168
	v_add_f32_e32 v169, 1.0, v169
	v_rcp_f32_e32 v166, v166
	v_rcp_f32_e32 v167, v167
	v_rcp_f32_e32 v168, v168
	v_rcp_f32_e32 v169, v169
	v_cvt_pk_bf16_f32 v152, v166, v167
	v_cvt_pk_bf16_f32 v153, v168, v169
	v_mul_f32_e32 v166, v165, v50
	v_mul_f32_e32 v167, v165, v51
	v_mul_f32_e32 v168, v165, v52
	v_mul_f32_e32 v169, v165, v53
	v_exp_f32_e32 v166, v166
	v_exp_f32_e32 v167, v167
	v_exp_f32_e32 v168, v168
	v_exp_f32_e32 v169, v169
	v_add_f32_e32 v166, 1.0, v166
	v_add_f32_e32 v167, 1.0, v167
	v_add_f32_e32 v168, 1.0, v168
	v_add_f32_e32 v169, 1.0, v169
	v_rcp_f32_e32 v166, v166
	v_rcp_f32_e32 v167, v167
	v_rcp_f32_e32 v168, v168
	v_rcp_f32_e32 v169, v169
	v_cvt_pk_bf16_f32 v154, v166, v167
	v_cvt_pk_bf16_f32 v155, v168, v169
	v_mul_f32_e32 v166, v165, v54
	v_mul_f32_e32 v167, v165, v55
	v_mul_f32_e32 v168, v165, v56
	v_mul_f32_e32 v169, v165, v57
	v_exp_f32_e32 v166, v166
	v_exp_f32_e32 v167, v167
	v_exp_f32_e32 v168, v168
	v_exp_f32_e32 v169, v169
	v_add_f32_e32 v166, 1.0, v166
	v_add_f32_e32 v167, 1.0, v167
	v_add_f32_e32 v168, 1.0, v168
	v_add_f32_e32 v169, 1.0, v169
	v_rcp_f32_e32 v166, v166
	v_rcp_f32_e32 v167, v167
	v_rcp_f32_e32 v168, v168
	v_rcp_f32_e32 v169, v169
	v_cvt_pk_bf16_f32 v156, v166, v167
	v_cvt_pk_bf16_f32 v157, v168, v169
	v_mul_f32_e32 v166, v165, v58
	v_mul_f32_e32 v167, v165, v59
	v_mul_f32_e32 v168, v165, v60
	v_mul_f32_e32 v169, v165, v61
	v_exp_f32_e32 v166, v166
	v_exp_f32_e32 v167, v167
	v_exp_f32_e32 v168, v168
	v_exp_f32_e32 v169, v169
	v_add_f32_e32 v166, 1.0, v166
	v_add_f32_e32 v167, 1.0, v167
	v_add_f32_e32 v168, 1.0, v168
	v_add_f32_e32 v169, 1.0, v169
	v_rcp_f32_e32 v166, v166
	v_rcp_f32_e32 v167, v167
	v_rcp_f32_e32 v168, v168
	v_rcp_f32_e32 v169, v169
	v_cvt_pk_bf16_f32 v158, v166, v167
	v_cvt_pk_bf16_f32 v159, v168, v169
	v_mul_f32_e32 v166, v165, v62
	v_mul_f32_e32 v167, v165, v63
	v_mul_f32_e32 v168, v165, v64
	v_mul_f32_e32 v169, v165, v65
	v_exp_f32_e32 v166, v166
	v_exp_f32_e32 v167, v167
	v_exp_f32_e32 v168, v168
	v_exp_f32_e32 v169, v169
	v_add_f32_e32 v166, 1.0, v166
	v_add_f32_e32 v167, 1.0, v167
	v_add_f32_e32 v168, 1.0, v168
	v_add_f32_e32 v169, 1.0, v169
	v_rcp_f32_e32 v166, v166
	v_rcp_f32_e32 v167, v167
	v_rcp_f32_e32 v168, v168
	v_rcp_f32_e32 v169, v169
	v_cvt_pk_bf16_f32 v160, v166, v167
	v_cvt_pk_bf16_f32 v161, v168, v169
	v_mov_b32_e32 v2, 0
	v_mov_b32_e32 v3, 0
	v_mov_b32_e32 v4, 0
	v_mov_b32_e32 v5, 0
	v_mov_b32_e32 v6, 0
	v_mov_b32_e32 v7, 0
	v_mov_b32_e32 v8, 0
	v_mov_b32_e32 v9, 0
	v_mov_b32_e32 v10, 0
	v_mov_b32_e32 v11, 0
	v_mov_b32_e32 v12, 0
	v_mov_b32_e32 v13, 0
	v_mov_b32_e32 v14, 0
	v_mov_b32_e32 v15, 0
	v_mov_b32_e32 v16, 0
	v_mov_b32_e32 v17, 0
	v_mov_b32_e32 v18, 0
	v_mov_b32_e32 v19, 0
	v_mov_b32_e32 v20, 0
	v_mov_b32_e32 v21, 0
	v_mov_b32_e32 v22, 0
	v_mov_b32_e32 v23, 0
	v_mov_b32_e32 v24, 0
	v_mov_b32_e32 v25, 0
	v_mov_b32_e32 v26, 0
	v_mov_b32_e32 v27, 0
	v_mov_b32_e32 v28, 0
	v_mov_b32_e32 v29, 0
	v_mov_b32_e32 v30, 0
	v_mov_b32_e32 v31, 0
	v_mov_b32_e32 v32, 0
	v_mov_b32_e32 v33, 0
	v_mov_b32_e32 v34, 0
	v_mov_b32_e32 v35, 0
	v_mov_b32_e32 v36, 0
	v_mov_b32_e32 v37, 0
	v_mov_b32_e32 v38, 0
	v_mov_b32_e32 v39, 0
	v_mov_b32_e32 v40, 0
	v_mov_b32_e32 v41, 0
	v_mov_b32_e32 v42, 0
	v_mov_b32_e32 v43, 0
	v_mov_b32_e32 v44, 0
	v_mov_b32_e32 v45, 0
	v_mov_b32_e32 v46, 0
	v_mov_b32_e32 v47, 0
	v_mov_b32_e32 v48, 0
	v_mov_b32_e32 v49, 0
	v_mov_b32_e32 v50, 0
	v_mov_b32_e32 v51, 0
	v_mov_b32_e32 v52, 0
	v_mov_b32_e32 v53, 0
	v_mov_b32_e32 v54, 0
	v_mov_b32_e32 v55, 0
	v_mov_b32_e32 v56, 0
	v_mov_b32_e32 v57, 0
	v_mov_b32_e32 v58, 0
	v_mov_b32_e32 v59, 0
	v_mov_b32_e32 v60, 0
	v_mov_b32_e32 v61, 0
	v_mov_b32_e32 v62, 0
	v_mov_b32_e32 v63, 0
	v_mov_b32_e32 v64, 0
	v_mov_b32_e32 v65, 0
	s_mov_b32 s74, 3
; #define BLOAD(A_, B_, kt) do { _Pragma("unroll") for (int i = 0; i < 4; ++i) { \
;     A_[i] = *(const u32x4*)((const char*)Ap + (aoff + (unsigned)(32 * i * lda + (kt) * 64) * 2u)); B_[i] = *(const u32x4*)((const char*)Wt + (woff + (unsigned)(32 * i * K + (kt) * 64) * 2u)); } } while (0)
; #define BLOAD(A_, B_, kt) do { _Pragma("unroll") for (int i = 0; i < 4; ++i) { \
;     A_[i] = *(const u32x4*)((const char*)Ap + (aoff + (unsigned)(32 * i * lda + (kt) * 64) * 2u)); B_[i] = *(const u32x4*)((const char*)Wt + (woff + (unsigned)(32 * i * K + (kt) * 64) * 2u)); } } while (0)
; #define BSTORE(A_, B_, buf) do { _Pragma("unroll") for (int i = 0; i < 4; ++i) { \
;     *(u32x4*)&As[(buf) * GBUF + (srow + 32 * i) * LDT + sc8] = A_[i]; \
;     *(u32x4*)&Bs[(buf) * GBUF + (srow + 32 * i) * LDT + sc8] = B_[i]; } } while (0)
; template <bool ROWNORM, int NK>
; DI void gemm_main_bf(const u16* __restrict__ Ap, int lda, const u16* __restrict__ Wt, f32x16 (&acc)[2][2], char* smem, float* rinv_s) {
;     ...
;   __builtin_amdgcn_s_setprio(0);
;   BLOAD(a0, b0, 0); BLOAD(a1, b1, 1);
;   __syncthreads();
;   BSTORE(a0, b0, 0);
;   BLOAD(a0, b0, 2);
;   __syncthreads();
; #pragma unroll
;   for (int kt = 0; kt < nk; kt += 2) {
;     BCOMP(0);
;     BSTORE(a1, b1, 1);
;     if (kt + 3 < nk) BLOAD(a1, b1, kt + 3);
;     __syncthreads();
;     BCOMP(1);
;     if (kt + 2 < nk) { BSTORE(a0, b0, 0); if (kt + 4 < nk) BLOAD(a0, b0, kt + 4); }
;     __syncthreads();
;   }
.Lbr_proj_k:
	s_waitcnt vmcnt(8)
	s_barrier
	ds_read_b128 v[208:211], v240 offset:0
	ds_read_b128 v[224:227], v241 offset:0
	ds_read_b128 v[228:231], v241 offset:1024
	ds_read_b128 v[232:235], v241 offset:2048
	ds_read_b128 v[236:239], v241 offset:3072
	s_add_u32 m0, s52, 0xc000
	s_add_u32 s28, s28, 0x40
	s_addc_u32 s29, s29, 0
	global_load_lds_dwordx4 v244, s[28:29]
	global_load_lds_dwordx4 v245, s[28:29] offset:1024
	s_add_u32 m0, s53, 0xc000
	s_add_u32 s30, s30, 0x40
	s_addc_u32 s31, s31, 0
	global_load_lds_dwordx4 v244, s[30:31]
	global_load_lds_dwordx4 v245, s[30:31] offset:1024
	ds_read_b128 v[212:215], v240 offset:1024
	ds_read_b128 v[216:219], v240 offset:2048
	ds_read_b128 v[220:223], v240 offset:3072
	s_waitcnt lgkmcnt(6)
	v_mfma_f32_16x16x32_bf16 v[2:5], v[224:227], v[208:211], v[2:5]
	s_waitcnt lgkmcnt(5)
	v_mfma_f32_16x16x32_bf16 v[6:9], v[228:231], v[208:211], v[6:9]
	s_waitcnt lgkmcnt(4)
	v_mfma_f32_16x16x32_bf16 v[10:13], v[232:235], v[208:211], v[10:13]
	s_waitcnt lgkmcnt(3)
	v_mfma_f32_16x16x32_bf16 v[14:17], v[236:239], v[208:211], v[14:17]
	s_waitcnt lgkmcnt(2)
	v_mfma_f32_16x16x32_bf16 v[18:21], v[224:227], v[212:215], v[18:21]
	v_mfma_f32_16x16x32_bf16 v[22:25], v[228:231], v[212:215], v[22:25]
	v_mfma_f32_16x16x32_bf16 v[26:29], v[232:235], v[212:215], v[26:29]
	v_mfma_f32_16x16x32_bf16 v[30:33], v[236:239], v[212:215], v[30:33]
	s_waitcnt lgkmcnt(1)
	v_mfma_f32_16x16x32_bf16 v[34:37], v[224:227], v[216:219], v[34:37]
	v_mfma_f32_16x16x32_bf16 v[38:41], v[228:231], v[216:219], v[38:41]
	v_mfma_f32_16x16x32_bf16 v[42:45], v[232:235], v[216:219], v[42:45]
	v_mfma_f32_16x16x32_bf16 v[46:49], v[236:239], v[216:219], v[46:49]
	s_waitcnt lgkmcnt(0)
	v_mfma_f32_16x16x32_bf16 v[50:53], v[224:227], v[220:223], v[50:53]
	v_mfma_f32_16x16x32_bf16 v[54:57], v[228:231], v[220:223], v[54:57]
	v_mfma_f32_16x16x32_bf16 v[58:61], v[232:235], v[220:223], v[58:61]
	v_mfma_f32_16x16x32_bf16 v[62:65], v[236:239], v[220:223], v[62:65]
	s_waitcnt vmcnt(8)
	s_barrier
	ds_read_b128 v[208:211], v240 offset:16384
	ds_read_b128 v[224:227], v241 offset:16384
	ds_read_b128 v[228:231], v241 offset:17408
	ds_read_b128 v[232:235], v241 offset:18432
	ds_read_b128 v[236:239], v241 offset:19456
	s_add_u32 m0, s52, 0x0
	s_add_u32 s28, s28, 0x40
	s_addc_u32 s29, s29, 0
	global_load_lds_dwordx4 v244, s[28:29]
	global_load_lds_dwordx4 v245, s[28:29] offset:1024
	s_add_u32 m0, s53, 0x0
	s_add_u32 s30, s30, 0x40
	s_addc_u32 s31, s31, 0
	global_load_lds_dwordx4 v244, s[30:31]
	global_load_lds_dwordx4 v245, s[30:31] offset:1024
	ds_read_b128 v[212:215], v240 offset:17408
	ds_read_b128 v[216:219], v240 offset:18432
	ds_read_b128 v[220:223], v240 offset:19456
	s_waitcnt lgkmcnt(6)
	v_mfma_f32_16x16x32_bf16 v[2:5], v[224:227], v[208:211], v[2:5]
	s_waitcnt lgkmcnt(5)
	v_mfma_f32_16x16x32_bf16 v[6:9], v[228:231], v[208:211], v[6:9]
	s_waitcnt lgkmcnt(4)
	v_mfma_f32_16x16x32_bf16 v[10:13], v[232:235], v[208:211], v[10:13]
	s_waitcnt lgkmcnt(3)
	v_mfma_f32_16x16x32_bf16 v[14:17], v[236:239], v[208:211], v[14:17]
	s_waitcnt lgkmcnt(2)
	v_mfma_f32_16x16x32_bf16 v[18:21], v[224:227], v[212:215], v[18:21]
	v_mfma_f32_16x16x32_bf16 v[22:25], v[228:231], v[212:215], v[22:25]
	v_mfma_f32_16x16x32_bf16 v[26:29], v[232:235], v[212:215], v[26:29]
	v_mfma_f32_16x16x32_bf16 v[30:33], v[236:239], v[212:215], v[30:33]
	s_waitcnt lgkmcnt(1)
	v_mfma_f32_16x16x32_bf16 v[34:37], v[224:227], v[216:219], v[34:37]
	v_mfma_f32_16x16x32_bf16 v[38:41], v[228:231], v[216:219], v[38:41]
	v_mfma_f32_16x16x32_bf16 v[42:45], v[232:235], v[216:219], v[42:45]
	v_mfma_f32_16x16x32_bf16 v[46:49], v[236:239], v[216:219], v[46:49]
	s_waitcnt lgkmcnt(0)
	v_mfma_f32_16x16x32_bf16 v[50:53], v[224:227], v[220:223], v[50:53]
	v_mfma_f32_16x16x32_bf16 v[54:57], v[228:231], v[220:223], v[54:57]
	v_mfma_f32_16x16x32_bf16 v[58:61], v[232:235], v[220:223], v[58:61]
	v_mfma_f32_16x16x32_bf16 v[62:65], v[236:239], v[220:223], v[62:65]
	s_waitcnt vmcnt(8)
	s_barrier
	ds_read_b128 v[208:211], v240 offset:32768
	ds_read_b128 v[224:227], v241 offset:32768
	ds_read_b128 v[228:231], v241 offset:33792
	ds_read_b128 v[232:235], v241 offset:34816
	ds_read_b128 v[236:239], v241 offset:35840
	s_add_u32 m0, s52, 0x4000
	s_add_u32 s28, s28, 0x40
	s_addc_u32 s29, s29, 0
	global_load_lds_dwordx4 v244, s[28:29]
	global_load_lds_dwordx4 v245, s[28:29] offset:1024
	s_add_u32 m0, s53, 0x4000
	s_add_u32 s30, s30, 0x40
	s_addc_u32 s31, s31, 0
	global_load_lds_dwordx4 v244, s[30:31]
	global_load_lds_dwordx4 v245, s[30:31] offset:1024
	ds_read_b128 v[212:215], v240 offset:33792
	ds_read_b128 v[216:219], v240 offset:34816
	ds_read_b128 v[220:223], v240 offset:35840
	s_waitcnt lgkmcnt(6)
	v_mfma_f32_16x16x32_bf16 v[2:5], v[224:227], v[208:211], v[2:5]
	s_waitcnt lgkmcnt(5)
	v_mfma_f32_16x16x32_bf16 v[6:9], v[228:231], v[208:211], v[6:9]
	s_waitcnt lgkmcnt(4)
	v_mfma_f32_16x16x32_bf16 v[10:13], v[232:235], v[208:211], v[10:13]
	s_waitcnt lgkmcnt(3)
	v_mfma_f32_16x16x32_bf16 v[14:17], v[236:239], v[208:211], v[14:17]
	s_waitcnt lgkmcnt(2)
	v_mfma_f32_16x16x32_bf16 v[18:21], v[224:227], v[212:215], v[18:21]
	v_mfma_f32_16x16x32_bf16 v[22:25], v[228:231], v[212:215], v[22:25]
	v_mfma_f32_16x16x32_bf16 v[26:29], v[232:235], v[212:215], v[26:29]
	v_mfma_f32_16x16x32_bf16 v[30:33], v[236:239], v[212:215], v[30:33]
	s_waitcnt lgkmcnt(1)
	v_mfma_f32_16x16x32_bf16 v[34:37], v[224:227], v[216:219], v[34:37]
	v_mfma_f32_16x16x32_bf16 v[38:41], v[228:231], v[216:219], v[38:41]
	v_mfma_f32_16x16x32_bf16 v[42:45], v[232:235], v[216:219], v[42:45]
	v_mfma_f32_16x16x32_bf16 v[46:49], v[236:239], v[216:219], v[46:49]
	s_waitcnt lgkmcnt(0)
	v_mfma_f32_16x16x32_bf16 v[50:53], v[224:227], v[220:223], v[50:53]
	v_mfma_f32_16x16x32_bf16 v[54:57], v[228:231], v[220:223], v[54:57]
	v_mfma_f32_16x16x32_bf16 v[58:61], v[232:235], v[220:223], v[58:61]
	v_mfma_f32_16x16x32_bf16 v[62:65], v[236:239], v[220:223], v[62:65]
	s_waitcnt vmcnt(8)
	s_barrier
; #define BLOAD(A_, B_, kt) do { _Pragma("unroll") for (int i = 0; i < 4; ++i) { \
;     A_[i] = *(const u32x4*)((const char*)Ap + (aoff + (unsigned)(32 * i * lda + (kt) * 64) * 2u)); B_[i] = *(const u32x4*)((const char*)Wt + (woff + (unsigned)(32 * i * K + (kt) * 64) * 2u)); } } while (0)
; #define BLOAD(A_, B_, kt) do { _Pragma("unroll") for (int i = 0; i < 4; ++i) { \
;     A_[i] = *(const u32x4*)((const char*)Ap + (aoff + (unsigned)(32 * i * lda + (kt) * 64) * 2u)); B_[i] = *(const u32x4*)((const char*)Wt + (woff + (unsigned)(32 * i * K + (kt) * 64) * 2u)); } } while (0)
; #define BSTORE(A_, B_, buf) do { _Pragma("unroll") for (int i = 0; i < 4; ++i) { \
;     *(u32x4*)&As[(buf) * GBUF + (srow + 32 * i) * LDT + sc8] = A_[i]; \
;     *(u32x4*)&Bs[(buf) * GBUF + (srow + 32 * i) * LDT + sc8] = B_[i]; } } while (0)
; template <bool ROWNORM, int NK>
; DI void gemm_main_bf(const u16* __restrict__ Ap, int lda, const u16* __restrict__ Wt, f32x16 (&acc)[2][2], char* smem, float* rinv_s) {
;     ...
;   __builtin_amdgcn_s_setprio(0);
;   BLOAD(a0, b0, 0); BLOAD(a1, b1, 1);
;   __syncthreads();
;   BSTORE(a0, b0, 0);
;   BLOAD(a0, b0, 2);
;   __syncthreads();
; #pragma unroll
;   for (int kt = 0; kt < nk; kt += 2) {
;     BCOMP(0);
;     BSTORE(a1, b1, 1);
;     if (kt + 3 < nk) BLOAD(a1, b1, kt + 3);
;     __syncthreads();
;     BCOMP(1);
;     if (kt + 2 < nk) { BSTORE(a0, b0, 0); if (kt + 4 < nk) BLOAD(a0, b0, kt + 4); }
;     __syncthreads();
;   }
	ds_read_b128 v[208:211], v240 offset:49152
	ds_read_b128 v[224:227], v241 offset:49152
	ds_read_b128 v[228:231], v241 offset:50176
	ds_read_b128 v[232:235], v241 offset:51200
	ds_read_b128 v[236:239], v241 offset:52224
	s_add_u32 m0, s52, 0x8000
	s_add_u32 s28, s28, 0x40
	s_addc_u32 s29, s29, 0
	global_load_lds_dwordx4 v244, s[28:29]
	global_load_lds_dwordx4 v245, s[28:29] offset:1024
	s_add_u32 m0, s53, 0x8000
	s_add_u32 s30, s30, 0x40
	s_addc_u32 s31, s31, 0
	global_load_lds_dwordx4 v244, s[30:31]
	global_load_lds_dwordx4 v245, s[30:31] offset:1024
	ds_read_b128 v[212:215], v240 offset:50176
	ds_read_b128 v[216:219], v240 offset:51200
	ds_read_b128 v[220:223], v240 offset:52224
	s_waitcnt lgkmcnt(6)
	v_mfma_f32_16x16x32_bf16 v[2:5], v[224:227], v[208:211], v[2:5]
	s_waitcnt lgkmcnt(5)
	v_mfma_f32_16x16x32_bf16 v[6:9], v[228:231], v[208:211], v[6:9]
	s_waitcnt lgkmcnt(4)
	v_mfma_f32_16x16x32_bf16 v[10:13], v[232:235], v[208:211], v[10:13]
	s_waitcnt lgkmcnt(3)
	v_mfma_f32_16x16x32_bf16 v[14:17], v[236:239], v[208:211], v[14:17]
	s_waitcnt lgkmcnt(2)
	v_mfma_f32_16x16x32_bf16 v[18:21], v[224:227], v[212:215], v[18:21]
	v_mfma_f32_16x16x32_bf16 v[22:25], v[228:231], v[212:215], v[22:25]
	v_mfma_f32_16x16x32_bf16 v[26:29], v[232:235], v[212:215], v[26:29]
	v_mfma_f32_16x16x32_bf16 v[30:33], v[236:239], v[212:215], v[30:33]
	s_waitcnt lgkmcnt(1)
	v_mfma_f32_16x16x32_bf16 v[34:37], v[224:227], v[216:219], v[34:37]
	v_mfma_f32_16x16x32_bf16 v[38:41], v[228:231], v[216:219], v[38:41]
	v_mfma_f32_16x16x32_bf16 v[42:45], v[232:235], v[216:219], v[42:45]
	v_mfma_f32_16x16x32_bf16 v[46:49], v[236:239], v[216:219], v[46:49]
	s_waitcnt lgkmcnt(0)
	v_mfma_f32_16x16x32_bf16 v[50:53], v[224:227], v[220:223], v[50:53]
	v_mfma_f32_16x16x32_bf16 v[54:57], v[228:231], v[220:223], v[54:57]
	v_mfma_f32_16x16x32_bf16 v[58:61], v[232:235], v[220:223], v[58:61]
	v_mfma_f32_16x16x32_bf16 v[62:65], v[236:239], v[220:223], v[62:65]
	s_sub_u32 s74, s74, 1
	s_cmp_lg_u32 s74, 0
	s_cbranch_scc1 .Lbr_proj_k
	s_waitcnt vmcnt(8)
	s_barrier
	ds_read_b128 v[208:211], v240 offset:0
	ds_read_b128 v[224:227], v241 offset:0
	ds_read_b128 v[228:231], v241 offset:1024
	ds_read_b128 v[232:235], v241 offset:2048
	ds_read_b128 v[236:239], v241 offset:3072
	s_add_u32 m0, s52, 0xc000
	s_add_u32 s28, s28, 0x40
	s_addc_u32 s29, s29, 0
	global_load_lds_dwordx4 v244, s[28:29]
	global_load_lds_dwordx4 v245, s[28:29] offset:1024
	s_add_u32 m0, s53, 0xc000
	s_add_u32 s30, s30, 0x40
	s_addc_u32 s31, s31, 0
	global_load_lds_dwordx4 v244, s[30:31]
	global_load_lds_dwordx4 v245, s[30:31] offset:1024
	ds_read_b128 v[212:215], v240 offset:1024
	ds_read_b128 v[216:219], v240 offset:2048
	ds_read_b128 v[220:223], v240 offset:3072
	s_waitcnt lgkmcnt(6)
	v_mfma_f32_16x16x32_bf16 v[2:5], v[224:227], v[208:211], v[2:5]
	s_waitcnt lgkmcnt(5)
	v_mfma_f32_16x16x32_bf16 v[6:9], v[228:231], v[208:211], v[6:9]
	s_waitcnt lgkmcnt(4)
	v_mfma_f32_16x16x32_bf16 v[10:13], v[232:235], v[208:211], v[10:13]
	s_waitcnt lgkmcnt(3)
	v_mfma_f32_16x16x32_bf16 v[14:17], v[236:239], v[208:211], v[14:17]
	s_waitcnt lgkmcnt(2)
	v_mfma_f32_16x16x32_bf16 v[18:21], v[224:227], v[212:215], v[18:21]
	v_mfma_f32_16x16x32_bf16 v[22:25], v[228:231], v[212:215], v[22:25]
	v_mfma_f32_16x16x32_bf16 v[26:29], v[232:235], v[212:215], v[26:29]
	v_mfma_f32_16x16x32_bf16 v[30:33], v[236:239], v[212:215], v[30:33]
	s_waitcnt lgkmcnt(1)
	v_mfma_f32_16x16x32_bf16 v[34:37], v[224:227], v[216:219], v[34:37]
	v_mfma_f32_16x16x32_bf16 v[38:41], v[228:231], v[216:219], v[38:41]
	v_mfma_f32_16x16x32_bf16 v[42:45], v[232:235], v[216:219], v[42:45]
	v_mfma_f32_16x16x32_bf16 v[46:49], v[236:239], v[216:219], v[46:49]
	s_waitcnt lgkmcnt(0)
	v_mfma_f32_16x16x32_bf16 v[50:53], v[224:227], v[220:223], v[50:53]
	v_mfma_f32_16x16x32_bf16 v[54:57], v[228:231], v[220:223], v[54:57]
	v_mfma_f32_16x16x32_bf16 v[58:61], v[232:235], v[220:223], v[58:61]
	v_mfma_f32_16x16x32_bf16 v[62:65], v[236:239], v[220:223], v[62:65]
	s_waitcnt vmcnt(8)
	s_barrier
	ds_read_b128 v[208:211], v240 offset:16384
	ds_read_b128 v[224:227], v241 offset:16384
	ds_read_b128 v[228:231], v241 offset:17408
	ds_read_b128 v[232:235], v241 offset:18432
	ds_read_b128 v[236:239], v241 offset:19456
	ds_read_b128 v[212:215], v240 offset:17408
	ds_read_b128 v[216:219], v240 offset:18432
	ds_read_b128 v[220:223], v240 offset:19456
	s_waitcnt lgkmcnt(6)
	v_mfma_f32_16x16x32_bf16 v[2:5], v[224:227], v[208:211], v[2:5]
	s_waitcnt lgkmcnt(5)
	v_mfma_f32_16x16x32_bf16 v[6:9], v[228:231], v[208:211], v[6:9]
	s_waitcnt lgkmcnt(4)
	v_mfma_f32_16x16x32_bf16 v[10:13], v[232:235], v[208:211], v[10:13]
	s_waitcnt lgkmcnt(3)
	v_mfma_f32_16x16x32_bf16 v[14:17], v[236:239], v[208:211], v[14:17]
	s_waitcnt lgkmcnt(2)
	v_mfma_f32_16x16x32_bf16 v[18:21], v[224:227], v[212:215], v[18:21]
	v_mfma_f32_16x16x32_bf16 v[22:25], v[228:231], v[212:215], v[22:25]
	v_mfma_f32_16x16x32_bf16 v[26:29], v[232:235], v[212:215], v[26:29]
	v_mfma_f32_16x16x32_bf16 v[30:33], v[236:239], v[212:215], v[30:33]
	s_waitcnt lgkmcnt(1)
	v_mfma_f32_16x16x32_bf16 v[34:37], v[224:227], v[216:219], v[34:37]
	v_mfma_f32_16x16x32_bf16 v[38:41], v[228:231], v[216:219], v[38:41]
	v_mfma_f32_16x16x32_bf16 v[42:45], v[232:235], v[216:219], v[42:45]
	v_mfma_f32_16x16x32_bf16 v[46:49], v[236:239], v[216:219], v[46:49]
	s_waitcnt lgkmcnt(0)
	v_mfma_f32_16x16x32_bf16 v[50:53], v[224:227], v[220:223], v[50:53]
	v_mfma_f32_16x16x32_bf16 v[54:57], v[228:231], v[220:223], v[54:57]
	v_mfma_f32_16x16x32_bf16 v[58:61], v[232:235], v[220:223], v[58:61]
	v_mfma_f32_16x16x32_bf16 v[62:65], v[236:239], v[220:223], v[62:65]
	s_waitcnt vmcnt(4)
	s_barrier
; #define BLOAD(A_, B_, kt) do { _Pragma("unroll") for (int i = 0; i < 4; ++i) { \
;     A_[i] = *(const u32x4*)((const char*)Ap + (aoff + (unsigned)(32 * i * lda + (kt) * 64) * 2u)); B_[i] = *(const u32x4*)((const char*)Wt + (woff + (unsigned)(32 * i * K + (kt) * 64) * 2u)); } } while (0)
; #define BLOAD(A_, B_, kt) do { _Pragma("unroll") for (int i = 0; i < 4; ++i) { \
;     A_[i] = *(const u32x4*)((const char*)Ap + (aoff + (unsigned)(32 * i * lda + (kt) * 64) * 2u)); B_[i] = *(const u32x4*)((const char*)Wt + (woff + (unsigned)(32 * i * K + (kt) * 64) * 2u)); } } while (0)
; #define BSTORE(A_, B_, buf) do { _Pragma("unroll") for (int i = 0; i < 4; ++i) { \
;     *(u32x4*)&As[(buf) * GBUF + (srow + 32 * i) * LDT + sc8] = A_[i]; \
;     *(u32x4*)&Bs[(buf) * GBUF + (srow + 32 * i) * LDT + sc8] = B_[i]; } } while (0)
; template <bool ROWNORM, int NK>
; DI void gemm_main_bf(const u16* __restrict__ Ap, int lda, const u16* __restrict__ Wt, f32x16 (&acc)[2][2], char* smem, float* rinv_s) {
;     ...
; #pragma unroll
;   for (int kt = 0; kt < nk; kt += 2) {
;     BCOMP(0);
;     BSTORE(a1, b1, 1);
;     if (kt + 3 < nk) BLOAD(a1, b1, kt + 3);
;     __syncthreads();
;     BCOMP(1);
;     if (kt + 2 < nk) { BSTORE(a0, b0, 0); if (kt + 4 < nk) BLOAD(a0, b0, kt + 4); }
;     __syncthreads();
;   }
; DI void tile_branch(const Params& p, int l, int tile, char* smem) {
;     ...
;   for (int br = 0; br < 3; ++br) {
;     unsigned gpk[2][2][8];
;     {
;       f32x16 accg[2][2]; zero_acc(accg);
;       gemm_main_bf<false, 16>((const u16*)(p.ws + OFF_XB) + (size_t)m0 * 1024, 1024,
;                               (const u16*)(p.ws + OFF_WIN + l * SZ_WIN) + (size_t)(5760 + br * 1024 + n0) * 1024, accg, smem, nullptr);
	ds_read_b128 v[208:211], v240 offset:32768
	ds_read_b128 v[224:227], v241 offset:32768
	ds_read_b128 v[228:231], v241 offset:33792
	ds_read_b128 v[232:235], v241 offset:34816
	ds_read_b128 v[236:239], v241 offset:35840
	ds_read_b128 v[212:215], v240 offset:33792
	ds_read_b128 v[216:219], v240 offset:34816
	ds_read_b128 v[220:223], v240 offset:35840
	s_waitcnt lgkmcnt(6)
	v_mfma_f32_16x16x32_bf16 v[2:5], v[224:227], v[208:211], v[2:5]
	s_waitcnt lgkmcnt(5)
	v_mfma_f32_16x16x32_bf16 v[6:9], v[228:231], v[208:211], v[6:9]
	s_waitcnt lgkmcnt(4)
	v_mfma_f32_16x16x32_bf16 v[10:13], v[232:235], v[208:211], v[10:13]
	s_waitcnt lgkmcnt(3)
	v_mfma_f32_16x16x32_bf16 v[14:17], v[236:239], v[208:211], v[14:17]
	s_waitcnt lgkmcnt(2)
	v_mfma_f32_16x16x32_bf16 v[18:21], v[224:227], v[212:215], v[18:21]
	v_mfma_f32_16x16x32_bf16 v[22:25], v[228:231], v[212:215], v[22:25]
	v_mfma_f32_16x16x32_bf16 v[26:29], v[232:235], v[212:215], v[26:29]
	v_mfma_f32_16x16x32_bf16 v[30:33], v[236:239], v[212:215], v[30:33]
	s_waitcnt lgkmcnt(1)
	v_mfma_f32_16x16x32_bf16 v[34:37], v[224:227], v[216:219], v[34:37]
	v_mfma_f32_16x16x32_bf16 v[38:41], v[228:231], v[216:219], v[38:41]
	v_mfma_f32_16x16x32_bf16 v[42:45], v[232:235], v[216:219], v[42:45]
	v_mfma_f32_16x16x32_bf16 v[46:49], v[236:239], v[216:219], v[46:49]
	s_waitcnt lgkmcnt(0)
	v_mfma_f32_16x16x32_bf16 v[50:53], v[224:227], v[220:223], v[50:53]
	v_mfma_f32_16x16x32_bf16 v[54:57], v[228:231], v[220:223], v[54:57]
	v_mfma_f32_16x16x32_bf16 v[58:61], v[232:235], v[220:223], v[58:61]
	v_mfma_f32_16x16x32_bf16 v[62:65], v[236:239], v[220:223], v[62:65]
	s_waitcnt vmcnt(0)
	s_barrier
	ds_read_b128 v[208:211], v240 offset:49152
	ds_read_b128 v[224:227], v241 offset:49152
	ds_read_b128 v[228:231], v241 offset:50176
	ds_read_b128 v[232:235], v241 offset:51200
	ds_read_b128 v[236:239], v241 offset:52224
	ds_read_b128 v[212:215], v240 offset:50176
	ds_read_b128 v[216:219], v240 offset:51200
	ds_read_b128 v[220:223], v240 offset:52224
	s_waitcnt lgkmcnt(6)
	v_mfma_f32_16x16x32_bf16 v[2:5], v[224:227], v[208:211], v[2:5]
	s_waitcnt lgkmcnt(5)
	v_mfma_f32_16x16x32_bf16 v[6:9], v[228:231], v[208:211], v[6:9]
	s_waitcnt lgkmcnt(4)
	v_mfma_f32_16x16x32_bf16 v[10:13], v[232:235], v[208:211], v[10:13]
	s_waitcnt lgkmcnt(3)
	v_mfma_f32_16x16x32_bf16 v[14:17], v[236:239], v[208:211], v[14:17]
	s_waitcnt lgkmcnt(2)
	v_mfma_f32_16x16x32_bf16 v[18:21], v[224:227], v[212:215], v[18:21]
	v_mfma_f32_16x16x32_bf16 v[22:25], v[228:231], v[212:215], v[22:25]
	v_mfma_f32_16x16x32_bf16 v[26:29], v[232:235], v[212:215], v[26:29]
	v_mfma_f32_16x16x32_bf16 v[30:33], v[236:239], v[212:215], v[30:33]
	s_waitcnt lgkmcnt(1)
	v_mfma_f32_16x16x32_bf16 v[34:37], v[224:227], v[216:219], v[34:37]
	v_mfma_f32_16x16x32_bf16 v[38:41], v[228:231], v[216:219], v[38:41]
	v_mfma_f32_16x16x32_bf16 v[42:45], v[232:235], v[216:219], v[42:45]
	v_mfma_f32_16x16x32_bf16 v[46:49], v[236:239], v[216:219], v[46:49]
	s_waitcnt lgkmcnt(0)
	v_mfma_f32_16x16x32_bf16 v[50:53], v[224:227], v[220:223], v[50:53]
	v_mfma_f32_16x16x32_bf16 v[54:57], v[228:231], v[220:223], v[54:57]
	v_mfma_f32_16x16x32_bf16 v[58:61], v[232:235], v[220:223], v[58:61]
	v_mfma_f32_16x16x32_bf16 v[62:65], v[236:239], v[220:223], v[62:65]
	s_add_u32 s46, s46, 0x200000
	s_addc_u32 s47, s47, 0
	s_add_u32 s48, s48, 0x1000000
	s_addc_u32 s49, s49, 0
	s_add_u32 s50, s50, 0x100000
	s_addc_u32 s51, s51, 0
	s_cmp_eq_u32 s75, 2
	s_cbranch_scc1 .Lbr_noprol
	s_mov_b64 s[28:29], s[44:45]
	s_mov_b64 s[30:31], s[46:47]
	s_add_u32 m0, s52, 0x0
	s_nop 0
	global_load_lds_dwordx4 v242, s[28:29]
	global_load_lds_dwordx4 v243, s[28:29] offset:1024
	s_add_u32 m0, s53, 0x0
	s_nop 0
	global_load_lds_dwordx4 v242, s[30:31]
	global_load_lds_dwordx4 v243, s[30:31] offset:1024
	s_add_u32 m0, s52, 0x4000
	s_add_u32 s28, s28, 0x40
	s_addc_u32 s29, s29, 0
	global_load_lds_dwordx4 v242, s[28:29]
	global_load_lds_dwordx4 v243, s[28:29] offset:1024
	s_add_u32 m0, s53, 0x4000
	s_add_u32 s30, s30, 0x40
	s_addc_u32 s31, s31, 0
	global_load_lds_dwordx4 v242, s[30:31]
	global_load_lds_dwordx4 v243, s[30:31] offset:1024
	s_add_u32 m0, s52, 0x8000
	s_add_u32 s28, s28, 0x40
	s_addc_u32 s29, s29, 0
	global_load_lds_dwordx4 v242, s[28:29]
	global_load_lds_dwordx4 v243, s[28:29] offset:1024
	s_add_u32 m0, s53, 0x8000
	s_add_u32 s30, s30, 0x40
	s_addc_u32 s31, s31, 0
	global_load_lds_dwordx4 v242, s[30:31]
	global_load_lds_dwordx4 v243, s[30:31] offset:1024
; DI unsigned pk2(float a, float b) { f2_t v = {a, b}; bf2_t r = __builtin_convertvector(v, bf2_t); return __builtin_bit_cast(unsigned, r); }
; DI int crow(int r, int hi) { return (r & 3) + 8 * (r >> 2) + 4 * hi; }
; DI void st8(u16* dst, const float (&v)[8]) { *(u32x4*)dst = pack8(v); }
; DI void tile_branch(const Params& p, int l, int tile, char* smem) {
;     ...
; #pragma unroll
;     for (int mt = 0; mt < 2; ++mt)
; #pragma unroll
;       for (int nt = 0; nt < 2; ++nt)
; #pragma unroll
;         for (int i = 0; i < 8; ++i) {
;           const float g0 = __uint_as_float(gpk[mt][nt][i] << 16), g1 = __uint_as_float(gpk[mt][nt][i] & 0xffff0000u);
;           const float a = __uint_as_float(upk[mt][nt][i] << 16) + g0 * acc[mt][nt][2 * i];
;           const float b = __uint_as_float(upk[mt][nt][i] & 0xffff0000u) + g1 * acc[mt][nt][2 * i + 1];
;           upk[mt][nt][i] = pk2(a, b);
;         }
;   }
;   __syncthreads();
; #pragma unroll
;   for (int mt = 0; mt < 2; ++mt)
; #pragma unroll
;     for (int nt = 0; nt < 2; ++nt)
; #pragma unroll
;       for (int i = 0; i < 8; ++i) {
;         const int cc = wn * 64 + nt * 32 + r32;
;         Cs[(wm * 64 + mt * 32 + crow(2 * i, hi)) * CSL + cc] = __uint_as_float(upk[mt][nt][i] << 16);
;         Cs[(wm * 64 + mt * 32 + crow(2 * i + 1, hi)) * CSL + cc] = __uint_as_float(upk[mt][nt][i] & 0xffff0000u);
;       }
;   __syncthreads();
;   const int row = tid >> 1, half = tid & 1; float v[8];
;   u16* dst = (u16*)(p.ws + OFF_U) + (size_t)(m0 + row) * 1024 + n0 + half * 64;
; #pragma unroll
;   for (int c8 = 0; c8 < 8; ++c8) { cs_ld8(Cs, row, half * 64 + c8 * 8, v); st8(dst + c8 * 8, v); }
.Lbr_noprol:
	v_lshlrev_b32_e32 v166, 16, v130
	v_and_b32_e32 v167, 0xffff0000, v130
	v_lshlrev_b32_e32 v168, 16, v131
	v_and_b32_e32 v169, 0xffff0000, v131
	v_fmac_f32_e32 v66, v166, v2
	v_fmac_f32_e32 v67, v167, v3
	v_fmac_f32_e32 v68, v168, v4
	v_fmac_f32_e32 v69, v169, v5
	v_lshlrev_b32_e32 v166, 16, v132
	v_and_b32_e32 v167, 0xffff0000, v132
	v_lshlrev_b32_e32 v168, 16, v133
	v_and_b32_e32 v169, 0xffff0000, v133
	v_fmac_f32_e32 v70, v166, v6
	v_fmac_f32_e32 v71, v167, v7
	v_fmac_f32_e32 v72, v168, v8
	v_fmac_f32_e32 v73, v169, v9
	v_lshlrev_b32_e32 v166, 16, v134
	v_and_b32_e32 v167, 0xffff0000, v134
	v_lshlrev_b32_e32 v168, 16, v135
	v_and_b32_e32 v169, 0xffff0000, v135
	v_fmac_f32_e32 v74, v166, v10
	v_fmac_f32_e32 v75, v167, v11
	v_fmac_f32_e32 v76, v168, v12
	v_fmac_f32_e32 v77, v169, v13
	v_lshlrev_b32_e32 v166, 16, v136
	v_and_b32_e32 v167, 0xffff0000, v136
	v_lshlrev_b32_e32 v168, 16, v137
	v_and_b32_e32 v169, 0xffff0000, v137
	v_fmac_f32_e32 v78, v166, v14
	v_fmac_f32_e32 v79, v167, v15
	v_fmac_f32_e32 v80, v168, v16
	v_fmac_f32_e32 v81, v169, v17
	v_lshlrev_b32_e32 v166, 16, v138
	v_and_b32_e32 v167, 0xffff0000, v138
	v_lshlrev_b32_e32 v168, 16, v139
	v_and_b32_e32 v169, 0xffff0000, v139
	v_fmac_f32_e32 v82, v166, v18
	v_fmac_f32_e32 v83, v167, v19
	v_fmac_f32_e32 v84, v168, v20
	v_fmac_f32_e32 v85, v169, v21
	v_lshlrev_b32_e32 v166, 16, v140
	v_and_b32_e32 v167, 0xffff0000, v140
	v_lshlrev_b32_e32 v168, 16, v141
	v_and_b32_e32 v169, 0xffff0000, v141
	v_fmac_f32_e32 v86, v166, v22
	v_fmac_f32_e32 v87, v167, v23
	v_fmac_f32_e32 v88, v168, v24
	v_fmac_f32_e32 v89, v169, v25
	v_lshlrev_b32_e32 v166, 16, v142
	v_and_b32_e32 v167, 0xffff0000, v142
	v_lshlrev_b32_e32 v168, 16, v143
	v_and_b32_e32 v169, 0xffff0000, v143
	v_fmac_f32_e32 v90, v166, v26
	v_fmac_f32_e32 v91, v167, v27
	v_fmac_f32_e32 v92, v168, v28
	v_fmac_f32_e32 v93, v169, v29
	v_lshlrev_b32_e32 v166, 16, v144
	v_and_b32_e32 v167, 0xffff0000, v144
	v_lshlrev_b32_e32 v168, 16, v145
	v_and_b32_e32 v169, 0xffff0000, v145
	v_fmac_f32_e32 v94, v166, v30
	v_fmac_f32_e32 v95, v167, v31
	v_fmac_f32_e32 v96, v168, v32
	v_fmac_f32_e32 v97, v169, v33
	v_lshlrev_b32_e32 v166, 16, v146
	v_and_b32_e32 v167, 0xffff0000, v146
	v_lshlrev_b32_e32 v168, 16, v147
	v_and_b32_e32 v169, 0xffff0000, v147
	v_fmac_f32_e32 v98, v166, v34
	v_fmac_f32_e32 v99, v167, v35
	v_fmac_f32_e32 v100, v168, v36
	v_fmac_f32_e32 v101, v169, v37
	v_lshlrev_b32_e32 v166, 16, v148
	v_and_b32_e32 v167, 0xffff0000, v148
	v_lshlrev_b32_e32 v168, 16, v149
	v_and_b32_e32 v169, 0xffff0000, v149
	v_fmac_f32_e32 v102, v166, v38
	v_fmac_f32_e32 v103, v167, v39
	v_fmac_f32_e32 v104, v168, v40
	v_fmac_f32_e32 v105, v169, v41
	v_lshlrev_b32_e32 v166, 16, v150
	v_and_b32_e32 v167, 0xffff0000, v150
	v_lshlrev_b32_e32 v168, 16, v151
	v_and_b32_e32 v169, 0xffff0000, v151
	v_fmac_f32_e32 v106, v166, v42
	v_fmac_f32_e32 v107, v167, v43
	v_fmac_f32_e32 v108, v168, v44
	v_fmac_f32_e32 v109, v169, v45
	v_lshlrev_b32_e32 v166, 16, v152
	v_and_b32_e32 v167, 0xffff0000, v152
	v_lshlrev_b32_e32 v168, 16, v153
	v_and_b32_e32 v169, 0xffff0000, v153
	v_fmac_f32_e32 v110, v166, v46
	v_fmac_f32_e32 v111, v167, v47
	v_fmac_f32_e32 v112, v168, v48
	v_fmac_f32_e32 v113, v169, v49
	v_lshlrev_b32_e32 v166, 16, v154
	v_and_b32_e32 v167, 0xffff0000, v154
	v_lshlrev_b32_e32 v168, 16, v155
	v_and_b32_e32 v169, 0xffff0000, v155
	v_fmac_f32_e32 v114, v166, v50
	v_fmac_f32_e32 v115, v167, v51
	v_fmac_f32_e32 v116, v168, v52
	v_fmac_f32_e32 v117, v169, v53
	v_lshlrev_b32_e32 v166, 16, v156
	v_and_b32_e32 v167, 0xffff0000, v156
	v_lshlrev_b32_e32 v168, 16, v157
	v_and_b32_e32 v169, 0xffff0000, v157
	v_fmac_f32_e32 v118, v166, v54
	v_fmac_f32_e32 v119, v167, v55
	v_fmac_f32_e32 v120, v168, v56
	v_fmac_f32_e32 v121, v169, v57
	v_lshlrev_b32_e32 v166, 16, v158
	v_and_b32_e32 v167, 0xffff0000, v158
	v_lshlrev_b32_e32 v168, 16, v159
	v_and_b32_e32 v169, 0xffff0000, v159
	v_fmac_f32_e32 v122, v166, v58
	v_fmac_f32_e32 v123, v167, v59
	v_fmac_f32_e32 v124, v168, v60
	v_fmac_f32_e32 v125, v169, v61
	v_lshlrev_b32_e32 v166, 16, v160
	v_and_b32_e32 v167, 0xffff0000, v160
	v_lshlrev_b32_e32 v168, 16, v161
	v_and_b32_e32 v169, 0xffff0000, v161
	v_fmac_f32_e32 v126, v166, v62
	v_fmac_f32_e32 v127, v167, v63
	v_fmac_f32_e32 v128, v168, v64
	v_fmac_f32_e32 v129, v169, v65
	s_add_i32 s75, s75, 1
	s_cmp_lt_u32 s75, 3
	s_cbranch_scc1 .Lbr_loop
	v_cvt_pk_bf16_f32 v66, v66, v67
	v_cvt_pk_bf16_f32 v67, v68, v69
	global_store_dwordx2 v249, v[66:67], s[22:23]
	v_cvt_pk_bf16_f32 v70, v70, v71
	v_cvt_pk_bf16_f32 v71, v72, v73
	global_store_dwordx2 v249, v[70:71], s[22:23] offset:32
	v_cvt_pk_bf16_f32 v74, v74, v75
	v_cvt_pk_bf16_f32 v75, v76, v77
	global_store_dwordx2 v249, v[74:75], s[22:23] offset:64
	v_cvt_pk_bf16_f32 v78, v78, v79
	v_cvt_pk_bf16_f32 v79, v80, v81
	global_store_dwordx2 v249, v[78:79], s[22:23] offset:96
	v_add_u32_e32 v249, 0x8000, v249
	v_cvt_pk_bf16_f32 v82, v82, v83
	v_cvt_pk_bf16_f32 v83, v84, v85
	global_store_dwordx2 v249, v[82:83], s[22:23]
	v_cvt_pk_bf16_f32 v86, v86, v87
	v_cvt_pk_bf16_f32 v87, v88, v89
	global_store_dwordx2 v249, v[86:87], s[22:23] offset:32
	v_cvt_pk_bf16_f32 v90, v90, v91
	v_cvt_pk_bf16_f32 v91, v92, v93
	global_store_dwordx2 v249, v[90:91], s[22:23] offset:64
	v_cvt_pk_bf16_f32 v94, v94, v95
	v_cvt_pk_bf16_f32 v95, v96, v97
	global_store_dwordx2 v249, v[94:95], s[22:23] offset:96
	v_add_u32_e32 v249, 0x8000, v249
	v_cvt_pk_bf16_f32 v98, v98, v99
	v_cvt_pk_bf16_f32 v99, v100, v101
	global_store_dwordx2 v249, v[98:99], s[22:23]
	v_cvt_pk_bf16_f32 v102, v102, v103
	v_cvt_pk_bf16_f32 v103, v104, v105
	global_store_dwordx2 v249, v[102:103], s[22:23] offset:32
	v_cvt_pk_bf16_f32 v106, v106, v107
	v_cvt_pk_bf16_f32 v107, v108, v109
	global_store_dwordx2 v249, v[106:107], s[22:23] offset:64
	v_cvt_pk_bf16_f32 v110, v110, v111
	v_cvt_pk_bf16_f32 v111, v112, v113
	global_store_dwordx2 v249, v[110:111], s[22:23] offset:96
	v_add_u32_e32 v249, 0x8000, v249
	v_cvt_pk_bf16_f32 v114, v114, v115
	v_cvt_pk_bf16_f32 v115, v116, v117
	global_store_dwordx2 v249, v[114:115], s[22:23]
	v_cvt_pk_bf16_f32 v118, v118, v119
	v_cvt_pk_bf16_f32 v119, v120, v121
	global_store_dwordx2 v249, v[118:119], s[22:23] offset:32
	v_cvt_pk_bf16_f32 v122, v122, v123
	v_cvt_pk_bf16_f32 v123, v124, v125
	global_store_dwordx2 v249, v[122:123], s[22:23] offset:64
	v_cvt_pk_bf16_f32 v126, v126, v127
	v_cvt_pk_bf16_f32 v127, v128, v129
	global_store_dwordx2 v249, v[126:127], s[22:23] offset:96
	s_add_i32 s17, s17, s78
	s_add_i32 s43, s43, s95
	s_cmpk_gt_i32 s17, 0x3ff
	s_cbranch_scc0 .LBB1_262
